# HGRN pass A and C: current-item loads issued before next-item prefetch with counted waits so the prefetch overlaps compute
# speedup vs baseline: 1.0301x; 1.0094x over previous
; DI void hgA_load(unsigned char* ws, int item, unsigned (&lf)[16], u32x4 (&ivw)[2]) {
;     const int tid = threadIdx.x, b = item >> 10, h = (item >> 6) & 15, c = item & 63, t0 = b * SEQ + c * 64, k = tid & 127, tq = tid >> 7;
;     const bf16_t* LOGF = (const bf16_t*)(ws + WS_LOGF);
; #pragma unroll
;     for (int i = 0; i < 16; ++i) lf[i] = LOGF[(size_t)(t0 + tq * 16 + i) * DM + h * 128 + k];
;     hg_iv_load((const bf16_t*)(ws + WS_IV), item, ivw);
; }
; __global__ void __launch_bounds__(512, 2) fwd_kernel(Args a) {
;     ...
;     if (IN(7)) {
;         __syncthreads();
;         int it = bx; unsigned lfa[16]; u32x4 iva[2];
;         if (it < 2048) hgA_load(ws, it, lfa, iva);
.LBB0_985:
	s_cmp_lt_i32 s84, 8
	s_cselect_b64 s[4:5], -1, 0
	s_and_b64 s[0:1], s[4:5], s[0:1]
	s_andn2_b64 vcc, exec, s[0:1]
	s_cbranch_vccnz .LBB0_993
	s_cmpk_gt_i32 s2, 0x7ff
	s_waitcnt vmcnt(0) lgkmcnt(0)
	s_barrier
	s_cbranch_scc1 .LBB0_993
	s_lshl_b32 s3, s2, 2
	s_lshl_b32 s4, s2, 6
	s_and_b32 s6, s3, 0xfffff000
	s_and_b32 s7, s4, 0xfc0
	s_add_u32 s4, s82, 0x8c80000
	v_lshrrev_b32_e32 v44, 3, v253
	s_addc_u32 s5, s83, 0
	v_and_b32_e32 v47, 0x70, v44
	s_or_b32 s6, s6, s7
	v_add_u32_e32 v0, s6, v47
	s_and_b32 s3, s3, 0xf00
	v_and_b32_e32 v45, 0x7f, v253
	s_add_u32 s6, s4, s3
	v_or_b32_e32 v8, 2, v0
	s_addc_u32 s7, s5, 0
	v_lshlrev_b32_e32 v40, 1, v45
	v_mov_b32_e32 v41, 0
	v_ashrrev_i32_e32 v9, 31, v8
	v_lshl_add_u64 v[2:3], s[6:7], 0, v[40:41]
	v_lshlrev_b64 v[8:9], 12, v[8:9]
	v_lshl_add_u64 v[16:17], v[2:3], 0, v[8:9]
	v_or_b32_e32 v8, 3, v0
	v_ashrrev_i32_e32 v9, 31, v8
	v_lshlrev_b64 v[8:9], 12, v[8:9]
	v_lshl_add_u64 v[18:19], v[2:3], 0, v[8:9]
	v_or_b32_e32 v8, 4, v0
	v_ashrrev_i32_e32 v9, 31, v8
	v_lshlrev_b64 v[8:9], 12, v[8:9]
	v_lshl_add_u64 v[20:21], v[2:3], 0, v[8:9]
	v_or_b32_e32 v8, 5, v0
	v_ashrrev_i32_e32 v9, 31, v8
	v_lshlrev_b64 v[8:9], 12, v[8:9]
	v_lshl_add_u64 v[22:23], v[2:3], 0, v[8:9]
	v_or_b32_e32 v8, 6, v0
	v_ashrrev_i32_e32 v9, 31, v8
	v_lshlrev_b64 v[8:9], 12, v[8:9]
	v_ashrrev_i32_e32 v1, 31, v0
	v_or_b32_e32 v6, 1, v0
	v_lshl_add_u64 v[24:25], v[2:3], 0, v[8:9]
	v_or_b32_e32 v8, 7, v0
	v_lshlrev_b64 v[4:5], 12, v[0:1]
	v_ashrrev_i32_e32 v7, 31, v6
	v_ashrrev_i32_e32 v9, 31, v8
	v_lshl_add_u64 v[4:5], v[2:3], 0, v[4:5]
	v_lshlrev_b64 v[6:7], 12, v[6:7]
	v_lshlrev_b64 v[8:9], 12, v[8:9]
	v_lshl_add_u64 v[6:7], v[2:3], 0, v[6:7]
	v_lshl_add_u64 v[26:27], v[2:3], 0, v[8:9]
	global_load_ushort v15, v[4:5], off
	global_load_ushort v14, v[6:7], off
	global_load_ushort v13, v[16:17], off
	global_load_ushort v12, v[18:19], off
	global_load_ushort v11, v[20:21], off
	global_load_ushort v10, v[22:23], off
	global_load_ushort v9, v[24:25], off
	global_load_ushort v8, v[26:27], off
	v_or_b32_e32 v4, 8, v0
	v_ashrrev_i32_e32 v5, 31, v4
	v_lshlrev_b64 v[4:5], 12, v[4:5]
	v_lshl_add_u64 v[24:25], v[2:3], 0, v[4:5]
	v_or_b32_e32 v4, 9, v0
	v_ashrrev_i32_e32 v5, 31, v4
	v_lshlrev_b64 v[4:5], 12, v[4:5]
	v_lshl_add_u64 v[26:27], v[2:3], 0, v[4:5]
	v_or_b32_e32 v4, 10, v0
	v_ashrrev_i32_e32 v5, 31, v4
	v_lshlrev_b64 v[4:5], 12, v[4:5]
	v_lshl_add_u64 v[28:29], v[2:3], 0, v[4:5]
	v_or_b32_e32 v4, 11, v0
	v_ashrrev_i32_e32 v5, 31, v4
	v_lshlrev_b64 v[4:5], 12, v[4:5]
	v_lshl_add_u64 v[30:31], v[2:3], 0, v[4:5]
	v_or_b32_e32 v4, 12, v0
	v_ashrrev_i32_e32 v5, 31, v4
	v_lshlrev_b64 v[4:5], 12, v[4:5]
	v_lshl_add_u64 v[32:33], v[2:3], 0, v[4:5]
	v_or_b32_e32 v4, 13, v0
	v_ashrrev_i32_e32 v5, 31, v4
	v_lshlrev_b64 v[4:5], 12, v[4:5]
	s_ashr_i32 s3, s2, 31
	v_lshl_add_u64 v[34:35], v[2:3], 0, v[4:5]
	v_or_b32_e32 v4, 14, v0
	v_or_b32_e32 v0, 15, v0
	s_lshl_b64 s[6:7], s[2:3], 14
	v_ashrrev_i32_e32 v1, 31, v0
	s_add_u32 s6, s82, s6
	v_lshlrev_b64 v[0:1], 12, v[0:1]
	s_addc_u32 s7, s83, s7
	v_lshlrev_b32_e32 v48, 4, v253
	v_mov_b32_e32 v49, v41
	v_lshl_add_u64 v[38:39], v[2:3], 0, v[0:1]
	v_lshl_add_u64 v[0:1], s[6:7], 0, v[48:49]
	s_mov_b32 s6, 0xcc80000
	v_add_co_u32_e32 v42, vcc, s6, v0
	v_ashrrev_i32_e32 v5, 31, v4
	s_nop 0
	v_addc_co_u32_e32 v43, vcc, 0, v1, vcc
	s_mov_b32 s6, 0xcc82000
	v_lshlrev_b64 v[4:5], 12, v[4:5]
	v_add_co_u32_e32 v50, vcc, s6, v0
	v_lshl_add_u64 v[36:37], v[2:3], 0, v[4:5]
	s_nop 0
	v_addc_co_u32_e32 v51, vcc, 0, v1, vcc
	global_load_dwordx4 v[4:7], v[42:43], off
	global_load_dwordx4 v[0:3], v[50:51], off
	global_load_ushort v23, v[24:25], off
	global_load_ushort v22, v[26:27], off
	global_load_ushort v21, v[28:29], off
	global_load_ushort v20, v[30:31], off
	global_load_ushort v19, v[32:33], off
	global_load_ushort v18, v[34:35], off
	global_load_ushort v17, v[36:37], off
	global_load_ushort v16, v[38:39], off
	s_add_u32 s21, s82, 0x2480000
	v_and_b32_e32 v24, 0x70, v48
	s_addc_u32 s22, s83, 0
	s_add_i32 s12, s2, s58
	v_add_u32_e32 v26, 0, v24
	v_add_u32_e32 v24, 0x200, v253
	s_ashr_i32 s13, s12, 31
	v_lshrrev_b32_e32 v24, 3, v24
	s_lshl_b32 s23, s12, 2
	s_lshl_b32 s26, s58, 2
	s_lshl_b32 s27, s12, 6
	s_lshl_b32 s28, s58, 6
	s_lshl_b32 s29, s12, 1
	s_lshl_b32 s30, s58, 1
	s_lshl_b64 s[12:13], s[12:13], 14
	v_mul_u32_u24_e32 v28, 0x90, v24
	v_lshrrev_b32_e32 v24, 2, v253
	s_add_u32 s12, s82, s12
	v_and_b32_e32 v30, 0xe0, v24
	v_bfe_u32 v24, v253, 5, 1
	s_addc_u32 s13, s83, s13
	v_lshlrev_b32_e32 v31, 9, v24
	v_lshl_add_u32 v46, v24, 4, 0
	v_lshl_add_u64 v[24:25], s[12:13], 0, v[48:49]
	s_mov_b64 s[12:13], 0xcc82000
	s_ashr_i32 s15, s58, 31
	s_mov_b32 s14, s58
	v_lshl_add_u64 v[48:49], v[24:25], 0, s[12:13]
	s_lshl_b64 s[12:13], s[14:15], 14
	s_lshl_b32 s31, s2, 14
	s_lshl_b32 s34, s58, 14
	s_lshl_b64 s[16:17], s[2:3], 9
	s_add_u32 s16, s82, s16
	v_lshl_add_u64 v[42:43], s[4:5], 0, v[40:41]
	v_lshlrev_b32_e32 v40, 2, v253
	v_lshl_add_u32 v53, v45, 2, 0
	s_movk_i32 s10, 0x8c
	s_addc_u32 s17, s83, s17
	v_mul_u32_u24_e32 v27, 0x90, v44
	s_movk_i32 s4, 0x80
	s_movk_i32 s6, 0xff
	s_movk_i32 s8, 0x17f
	v_mad_u32_u24 v29, v45, s10, v53
	v_and_b32_e32 v54, 31, v253
	v_lshl_add_u64 v[24:25], s[16:17], 0, v[40:41]
	s_mov_b64 s[16:17], 0x300000
	s_mov_b32 s11, 0
	v_add_u32_e32 v52, 0, v40
	s_movk_i32 s20, 0x90
	v_cmp_gt_u32_e64 s[4:5], s4, v253
	v_cmp_lt_u32_e64 s[6:7], s6, v253
	v_cmp_lt_u32_e64 s[8:9], s8, v253
	v_lshlrev_b32_e32 v44, 1, v54
	v_lshl_add_u64 v[50:51], v[24:25], 0, s[16:17]
	s_lshl_b64 s[14:15], s[14:15], 9
	v_add_u32_e32 v55, v26, v27
	s_mov_b32 s3, 0x3f317218
	v_add_u32_e32 v56, v26, v28
	v_add_u32_e32 v57, v29, v30
	v_lshlrev_b32_e32 v58, 1, v31
	s_movk_i32 s35, 0x1000
	s_mov_b32 s37, s2
	s_waitcnt vmcnt(9)
	v_mov_b64_e32 v[38:39], v[6:7]
	s_waitcnt vmcnt(8)
	v_mov_b64_e32 v[34:35], v[2:3]
	v_mov_b64_e32 v[32:33], v[0:1]
	v_mov_b64_e32 v[36:37], v[4:5]
	s_waitcnt vmcnt(0)
	s_branch .LBB0_989
; #define LAS __attribute__((address_space(3)))
; DI unsigned pk2(float lo, float hi) { f32x2 v = {lo, hi}; bf2_t b = __builtin_convertvector(v, bf2_t); return __builtin_bit_cast(unsigned, b); }
; DI bf16_t* ds_item_ptr(unsigned char* ws, unsigned char* ob, int b, int h, int c) { return (bf16_t*)(b == 0 ? ws + WS_DS0 : ob) + ((size_t)(h * 64 + c)) * 16384; }
; DI void hgA_item(LAS unsigned char* lds, unsigned char* ws, unsigned char* ob, int item, const unsigned (&lfr)[16], const u32x4 (&ivw)[2], const float* lbp) {
;     ...
;     for (int ks = 0; ks < 4; ++ks) {
;         const bf16x8 av = *(const LAS bf16x8*)(VTs + (32 * vb + r) * TROW + (16 * ks + 8 * h2) * 2);
;         const bf16x8 b0 = *(const LAS bf16x8*)(KTs + (64 * kb2 + 2 * r) * TROW + (16 * ks + 8 * h2) * 2);
;         const bf16x8 b1 = *(const LAS bf16x8*)(KTs + (64 * kb2 + 2 * r + 1) * TROW + (16 * ks + 8 * h2) * 2);
;         a0 = __builtin_amdgcn_mfma_f32_32x32x16_bf16(av, b0, a0, 0, 0, 0);
;         a1 = __builtin_amdgcn_mfma_f32_32x32x16_bf16(av, b1, a1, 0, 0, 0);
;     }
;     bf16_t* D = ds_item_ptr(ws, ob, b, h, c);
; #pragma unroll
;     for (int i = 0; i < 16; ++i) {
;         const int v = 32 * vb + (i & 3) + 8 * (i >> 2) + 4 * h2;
;         *(unsigned*)(D + v * 128 + 64 * kb2 + 2 * r) = pk2(a0[i], a1[i]);
;     }
;     __syncthreads();
; __global__ void __launch_bounds__(512, 2) fwd_kernel(Args a) {
;     ...
; #pragma unroll
;             for (int i = 0; i < 16; ++i) lfa[i] = lfb[i];
;             iva[0] = ivb[0]; iva[1] = ivb[1]; it = nx;
.LBB0_988:
	s_or_b64 exec, exec, s[18:19]
	s_lshr_b32 s18, s38, 1
	s_and_b32 s39, s18, 0x60
	v_or_b32_e32 v0, s39, v54
	v_mad_u32_u24 v40, v0, s20, v46
	s_waitcnt lgkmcnt(0)
	s_barrier
	ds_read_b128 v[16:19], v40 offset:18432
	s_lshr_b32 s18, s38, 2
	s_and_b32 s38, s18, 0x3fffffc0
	v_or_b32_e32 v0, s38, v44
	v_mad_u64_u32 v[92:93], s[18:19], v0, s20, v[46:47]
	ds_read_b128 v[0:3], v92
	ds_read_b128 v[76:79], v40 offset:18464
	ds_read_b128 v[80:83], v92 offset:32
	s_waitcnt lgkmcnt(2)
	v_mfma_f32_32x32x16_bf16 v[0:15], v[16:19], v[0:3], 0
	ds_read_b128 v[20:23], v92 offset:144
	ds_read_b128 v[84:87], v92 offset:176
	s_cmpk_lt_u32 s37, 0x400
	s_cselect_b32 s18, s22, s81
	s_cselect_b32 s19, s21, s80
	s_and_b32 s37, s31, 0xfc000
	s_lshl_b32 s10, s10, 21
	s_lshl_b32 s37, s37, 1
	s_waitcnt lgkmcnt(1)
	v_mfma_f32_32x32x16_bf16 v[16:31], v[16:19], v[20:23], 0
	s_or_b32 s10, s10, s37
	s_add_u32 s10, s19, s10
	s_addc_u32 s19, s18, 0
	s_lshl_b32 s18, s38, 1
	s_add_u32 s18, s10, s18
	s_addc_u32 s19, s19, 0
	s_add_i32 s23, s23, s26
	v_mfma_f32_32x32x16_bf16 v[0:15], v[76:79], v[80:83], v[0:15]
	s_add_i32 s27, s27, s28
	s_add_i32 s29, s29, s30
	v_lshl_add_u64 v[48:49], v[48:49], 0, s[12:13]
	s_add_i32 s31, s31, s34
	v_lshl_add_u64 v[50:51], v[50:51], 0, s[14:15]
	s_mov_b32 s37, s36
	s_waitcnt lgkmcnt(0)
	v_mfma_f32_32x32x16_bf16 v[16:31], v[76:79], v[84:87], v[16:31]
	ds_read_b128 v[76:79], v40 offset:18496
	ds_read_b128 v[80:83], v92 offset:64
	ds_read_b128 v[84:87], v40 offset:18528
	ds_read_b128 v[88:91], v92 offset:96
	v_lshlrev_b32_e32 v40, 1, v44
	s_waitcnt lgkmcnt(2)
	v_mfma_f32_32x32x16_bf16 v[0:15], v[76:79], v[80:83], v[0:15]
	ds_read_b128 v[80:83], v92 offset:208
	ds_read_b128 v[92:95], v92 offset:240
	s_waitcnt lgkmcnt(1)
	v_mfma_f32_32x32x16_bf16 v[16:31], v[76:79], v[80:83], v[16:31]
	v_lshl_add_u64 v[76:77], s[18:19], 0, v[40:41]
	v_lshl_or_b32 v40, s39, 8, v58
	v_lshl_add_u64 v[76:77], v[76:77], 0, v[40:41]
	v_mfma_f32_32x32x16_bf16 v[0:15], v[84:87], v[88:91], v[0:15]
	s_waitcnt lgkmcnt(0)
	v_mfma_f32_32x32x16_bf16 v[16:31], v[84:87], v[92:95], v[16:31]
	s_nop 11
	v_cvt_pk_bf16_f32 v0, v0, v16
	global_store_dword v[76:77], v0, off
	v_cvt_pk_bf16_f32 v0, v1, v17
	global_store_dword v[76:77], v0, off offset:256
	v_cvt_pk_bf16_f32 v0, v2, v18
	global_store_dword v[76:77], v0, off offset:512
	v_cvt_pk_bf16_f32 v0, v3, v19
	global_store_dword v[76:77], v0, off offset:768
	v_cvt_pk_bf16_f32 v0, v4, v20
	global_store_dword v[76:77], v0, off offset:2048
	v_cvt_pk_bf16_f32 v0, v5, v21
	global_store_dword v[76:77], v0, off offset:2304
	v_cvt_pk_bf16_f32 v0, v6, v22
	global_store_dword v[76:77], v0, off offset:2560
	v_cvt_pk_bf16_f32 v0, v7, v23
	global_store_dword v[76:77], v0, off offset:2816
	v_add_co_u32_e32 v0, vcc, s35, v76
	v_cvt_pk_bf16_f32 v2, v8, v24
	s_nop 0
	v_addc_co_u32_e32 v1, vcc, 0, v77, vcc
	global_store_dword v[0:1], v2, off
	v_cvt_pk_bf16_f32 v2, v9, v25
	global_store_dword v[0:1], v2, off offset:256
	v_cvt_pk_bf16_f32 v2, v10, v26
	global_store_dword v[0:1], v2, off offset:512
	v_cvt_pk_bf16_f32 v2, v11, v27
	global_store_dword v[0:1], v2, off offset:768
	v_cvt_pk_bf16_f32 v2, v12, v28
	global_store_dword v[0:1], v2, off offset:2048
	v_cvt_pk_bf16_f32 v2, v13, v29
	global_store_dword v[0:1], v2, off offset:2304
	v_cvt_pk_bf16_f32 v2, v14, v30
	global_store_dword v[0:1], v2, off offset:2560
	v_cvt_pk_bf16_f32 v2, v15, v31
	global_store_dword v[0:1], v2, off offset:2816
	s_waitcnt vmcnt(16)
	v_mov_b64_e32 v[4:5], v[36:37]
	v_mov_b64_e32 v[0:1], v[32:33]
	s_andn2_b64 vcc, exec, s[16:17]
	v_mov_b64_e32 v[6:7], v[38:39]
	v_mov_b64_e32 v[2:3], v[34:35]
	v_mov_b32_e32 v15, v59
	v_mov_b32_e32 v14, v60
	v_mov_b32_e32 v13, v61
	v_mov_b32_e32 v12, v62
	v_mov_b32_e32 v11, v63
	v_mov_b32_e32 v10, v64
	v_mov_b32_e32 v9, v65
	v_mov_b32_e32 v8, v66
	v_mov_b32_e32 v23, v67
	v_mov_b32_e32 v22, v68
	v_mov_b32_e32 v21, v69
	v_mov_b32_e32 v20, v70
	v_mov_b32_e32 v19, v71
	v_mov_b32_e32 v18, v72
	v_mov_b32_e32 v17, v73
	v_mov_b32_e32 v16, v74
	s_barrier
	s_cbranch_vccz .LBB0_993
; #define LAS __attribute__((address_space(3)))
; DI float h2f(unsigned short u) { return (float)__builtin_bit_cast(_Float16, u); }
; DI void hgA_load(unsigned char* ws, int item, unsigned (&lf)[16], u32x4 (&ivw)[2]) {
;     const int tid = threadIdx.x, b = item >> 10, h = (item >> 6) & 15, c = item & 63, t0 = b * SEQ + c * 64, k = tid & 127, tq = tid >> 7;
;     const bf16_t* LOGF = (const bf16_t*)(ws + WS_LOGF);
; #pragma unroll
;     for (int i = 0; i < 16; ++i) lf[i] = LOGF[(size_t)(t0 + tq * 16 + i) * DM + h * 128 + k];
;     hg_iv_load((const bf16_t*)(ws + WS_IV), item, ivw);
; }
; DI void hgC_load(unsigned char* ws, int item, unsigned (&lf)[16], unsigned (&qv)[16], u32x4 (&ivw)[2]) {
;     const int tid = threadIdx.x, b = item >> 10, h = (item >> 6) & 15, c = item & 63, t0 = b * SEQ + c * 64, kp = tid & 63, tq = tid >> 6;
;     const bf16_t* LOGF = (const bf16_t*)(ws + WS_LOGF);
;     const bf16_t* Q2 = (const bf16_t*)(ws + WS_Q2);
; #pragma unroll
;     for (int i = 0; i < 8; ++i) { const size_t o = (size_t)(t0 + tq * 8 + i) * DM + h * 128 + 2 * kp; lf[i] = *(const unsigned*)(LOGF + o); qv[i] = *(const unsigned*)(Q2 + o); }
;     hg_iv_load((const bf16_t*)(ws + WS_IV), item, ivw);
; }
; DI void hgA_item(LAS unsigned char* lds, unsigned char* ws, unsigned char* ob, int item, const unsigned (&lfr)[16], const u32x4 (&ivw)[2], const float* lbp) {
;     const int tid = threadIdx.x, lane = tid & 63, wid = __builtin_amdgcn_readfirstlane(tid >> 6);
;     const int b = item >> 10, h = (item >> 6) & 15, c = item & 63;
;     const int t0 = b * SEQ + c * 64;
;     LAS unsigned char* KTs = lds;
;     LAS unsigned char* VTs = lds + 128 * TROW;
;     LAS float* tot = (LAS float*)(lds + 2 * 128 * TROW);
;     const int k = tid & 127, tq = tid >> 7;
;     float lf[16], kk[16];
;     { const float lbk = lbp[h * 128 + (tid & 127)];
; #pragma unroll
;       for (int i = 0; i < 16; ++i) { const float om = (1.f - lbk) * sigmoidf_(-h2f((unsigned short)lfr[i])); kk[i] = om; lf[i] = flog(1.f - om); } }
; __global__ void __launch_bounds__(512, 2) fwd_kernel(Args a) {
;     ...
;         while (it < 2048) {
;             const int nx = it + G; unsigned lfb[16]; u32x4 ivb[2];
; #pragma unroll
;             for (int i = 0; i < 16; ++i) lfb[i] = 0u;
;             ivb[0] = iva[0]; ivb[1] = iva[1];
;             if (nx < 2048) hgA_load(ws, nx, lfb, ivb);
.LBB0_989:
	s_add_i32 s36, s37, s58
	s_cmpk_gt_i32 s36, 0x7ff
	s_cselect_b64 s[16:17], -1, 0
	s_and_b64 vcc, exec, s[16:17]
	v_mov_b32_e32 v59, 0
	v_mov_b32_e32 v60, 0
	v_mov_b32_e32 v61, 0
	v_mov_b32_e32 v62, 0
	v_mov_b32_e32 v63, 0
	v_mov_b32_e32 v64, 0
	v_mov_b32_e32 v65, 0
	v_mov_b32_e32 v66, 0
	v_mov_b32_e32 v67, 0
	v_mov_b32_e32 v68, 0
	v_mov_b32_e32 v69, 0
	v_mov_b32_e32 v70, 0
	v_mov_b32_e32 v71, 0
	v_mov_b32_e32 v72, 0
	v_mov_b32_e32 v73, 0
	v_mov_b32_e32 v74, 0
	s_bfe_u32 s98, s37, 0x40006
	v_lshlrev_b32_e32 v100, 2, v45
	v_lshl_or_b32 v100, s98, 9, v100
	global_load_dword v100, v100, s[24:25]
	s_cbranch_vccnz .LBB0_991
	s_and_b32 s10, s23, 0xfffff000
	s_and_b32 s18, s27, 0xfc0
	s_or_b32 s10, s10, s18
	v_add_u32_e32 v24, s10, v47
	s_and_b32 s10, s29, 0x780
	v_or_b32_e32 v60, 6, v24
	s_lshl_b32 s10, s10, 1
	v_ashrrev_i32_e32 v61, 31, v60
	v_lshl_add_u64 v[26:27], v[42:43], 0, s[10:11]
	v_lshlrev_b64 v[60:61], 12, v[60:61]
	v_lshl_add_u64 v[66:67], v[26:27], 0, v[60:61]
	v_or_b32_e32 v60, 7, v24
	v_ashrrev_i32_e32 v25, 31, v24
	v_or_b32_e32 v30, 1, v24
	v_or_b32_e32 v32, 2, v24
	v_or_b32_e32 v34, 3, v24
	v_or_b32_e32 v36, 4, v24
	v_or_b32_e32 v38, 5, v24
	v_ashrrev_i32_e32 v61, 31, v60
	v_lshlrev_b64 v[28:29], 12, v[24:25]
	v_ashrrev_i32_e32 v31, 31, v30
	v_ashrrev_i32_e32 v33, 31, v32
	v_ashrrev_i32_e32 v35, 31, v34
	v_ashrrev_i32_e32 v37, 31, v36
	v_ashrrev_i32_e32 v39, 31, v38
	v_lshlrev_b64 v[60:61], 12, v[60:61]
	v_lshl_add_u64 v[28:29], v[26:27], 0, v[28:29]
	v_lshlrev_b64 v[30:31], 12, v[30:31]
	v_lshlrev_b64 v[32:33], 12, v[32:33]
	v_lshlrev_b64 v[34:35], 12, v[34:35]
	v_lshlrev_b64 v[36:37], 12, v[36:37]
	v_lshlrev_b64 v[38:39], 12, v[38:39]
	v_lshl_add_u64 v[68:69], v[26:27], 0, v[60:61]
	v_lshl_add_u64 v[30:31], v[26:27], 0, v[30:31]
	v_lshl_add_u64 v[32:33], v[26:27], 0, v[32:33]
	v_lshl_add_u64 v[34:35], v[26:27], 0, v[34:35]
	v_lshl_add_u64 v[36:37], v[26:27], 0, v[36:37]
	v_lshl_add_u64 v[38:39], v[26:27], 0, v[38:39]
	global_load_ushort v59, v[28:29], off
	global_load_ushort v60, v[30:31], off
	global_load_ushort v61, v[32:33], off
	global_load_ushort v62, v[34:35], off
	global_load_ushort v63, v[36:37], off
	global_load_ushort v64, v[38:39], off
	global_load_ushort v65, v[66:67], off
	s_nop 0
	global_load_ushort v66, v[68:69], off
	v_or_b32_e32 v28, 8, v24
	v_or_b32_e32 v68, 14, v24
	v_ashrrev_i32_e32 v29, 31, v28
	v_or_b32_e32 v30, 9, v24
	v_or_b32_e32 v32, 10, v24
	v_or_b32_e32 v34, 11, v24
	v_or_b32_e32 v36, 12, v24
	v_or_b32_e32 v38, 13, v24
	v_ashrrev_i32_e32 v69, 31, v68
	v_or_b32_e32 v24, 15, v24
	v_lshlrev_b64 v[28:29], 12, v[28:29]
	v_ashrrev_i32_e32 v31, 31, v30
	v_ashrrev_i32_e32 v33, 31, v32
	v_ashrrev_i32_e32 v35, 31, v34
	v_ashrrev_i32_e32 v37, 31, v36
	v_ashrrev_i32_e32 v39, 31, v38
	v_lshlrev_b64 v[68:69], 12, v[68:69]
	v_ashrrev_i32_e32 v25, 31, v24
	v_lshl_add_u64 v[28:29], v[26:27], 0, v[28:29]
	v_lshlrev_b64 v[30:31], 12, v[30:31]
	v_lshlrev_b64 v[32:33], 12, v[32:33]
	v_lshlrev_b64 v[34:35], 12, v[34:35]
	v_lshlrev_b64 v[36:37], 12, v[36:37]
	v_lshlrev_b64 v[38:39], 12, v[38:39]
	v_lshl_add_u64 v[74:75], v[26:27], 0, v[68:69]
	v_lshlrev_b64 v[24:25], 12, v[24:25]
	v_lshl_add_u64 v[30:31], v[26:27], 0, v[30:31]
	v_lshl_add_u64 v[32:33], v[26:27], 0, v[32:33]
	v_lshl_add_u64 v[34:35], v[26:27], 0, v[34:35]
	v_lshl_add_u64 v[36:37], v[26:27], 0, v[36:37]
	v_lshl_add_u64 v[38:39], v[26:27], 0, v[38:39]
	v_lshl_add_u64 v[24:25], v[26:27], 0, v[24:25]
	global_load_ushort v67, v[28:29], off
	global_load_ushort v68, v[30:31], off
	global_load_ushort v69, v[32:33], off
	global_load_ushort v70, v[34:35], off
	global_load_ushort v71, v[36:37], off
	global_load_ushort v72, v[38:39], off
	global_load_ushort v73, v[74:75], off
	s_nop 0
	global_load_ushort v74, v[24:25], off
	v_add_co_u32_e32 v24, vcc, 0xffffe000, v48
	s_nop 1
	v_addc_co_u32_e32 v25, vcc, -1, v49, vcc
	global_load_dwordx4 v[36:39], v[24:25], off
	global_load_dwordx4 v[32:35], v[48:49], off
.LBB0_991:
	s_bfe_u32 s10, s37, 0x40006
	v_cvt_f32_f16_e32 v23, v23
	v_cvt_f32_f16_e32 v22, v22
	v_cvt_f32_f16_e32 v17, v17
	v_cvt_f32_f16_e32 v16, v16
	v_cvt_f32_f16_e32 v12, v12
	v_cvt_f32_f16_e32 v11, v11
	v_cvt_f32_f16_e32 v21, v21
	v_cvt_f32_f16_e32 v20, v20
	v_cvt_f32_f16_e32 v19, v19
	v_cvt_f32_f16_e32 v18, v18
	v_mul_f32_e32 v23, 0x3fb8aa3b, v23
	v_mul_f32_e32 v22, 0x3fb8aa3b, v22
	v_mul_f32_e32 v17, 0x3fb8aa3b, v17
	v_mul_f32_e32 v16, 0x3fb8aa3b, v16
	v_exp_f32_e32 v23, v23
	v_exp_f32_e32 v22, v22
	v_exp_f32_e32 v17, v17
	v_exp_f32_e32 v16, v16
	v_mul_f32_e32 v12, 0x3fb8aa3b, v12
	v_mul_f32_e32 v11, 0x3fb8aa3b, v11
	v_mul_f32_e32 v21, 0x3fb8aa3b, v21
	v_mul_f32_e32 v20, 0x3fb8aa3b, v20
	v_mul_f32_e32 v19, 0x3fb8aa3b, v19
	v_mul_f32_e32 v18, 0x3fb8aa3b, v18
	v_exp_f32_e32 v12, v12
	v_exp_f32_e32 v11, v11
	v_exp_f32_e32 v21, v21
	v_exp_f32_e32 v20, v20
	v_cvt_f32_f16_e32 v15, v15
	v_cvt_f32_f16_e32 v14, v14
	v_exp_f32_e32 v19, v19
	v_exp_f32_e32 v25, v18
	v_cvt_f32_f16_e32 v13, v13
	v_cvt_f32_f16_e32 v10, v10
	v_cvt_f32_f16_e32 v9, v9
	v_cvt_f32_f16_e32 v8, v8
	v_add_f32_e32 v23, 1.0, v23
	v_add_f32_e32 v22, 1.0, v22
	v_add_f32_e32 v30, 1.0, v17
	v_add_f32_e32 v31, 1.0, v16
	v_rcp_f32_e32 v16, v23
	v_rcp_f32_e32 v17, v22
	v_rcp_f32_e32 v22, v30
	v_rcp_f32_e32 v23, v31
	v_add_f32_e32 v12, 1.0, v12
	v_add_f32_e32 v18, 1.0, v11
	v_add_f32_e32 v21, 1.0, v21
	v_add_f32_e32 v20, 1.0, v20
	v_mul_f32_e32 v15, 0x3fb8aa3b, v15
	v_mul_f32_e32 v14, 0x3fb8aa3b, v14
	v_add_f32_e32 v29, 1.0, v19
	v_rcp_f32_e32 v11, v12
	v_rcp_f32_e32 v12, v18
	v_rcp_f32_e32 v18, v21
	v_rcp_f32_e32 v19, v20
	v_add_f32_e32 v21, 1.0, v25
	v_mul_f32_e32 v13, 0x3fb8aa3b, v13
	v_mul_f32_e32 v10, 0x3fb8aa3b, v10
	v_mul_f32_e32 v9, 0x3fb8aa3b, v9
	v_mul_f32_e32 v8, 0x3fb8aa3b, v8
	v_exp_f32_e32 v15, v15
	v_exp_f32_e32 v14, v14
	v_rcp_f32_e32 v20, v29
	v_rcp_f32_e32 v21, v21
	v_exp_f32_e32 v13, v13
	v_exp_f32_e32 v10, v10
	v_exp_f32_e32 v9, v9
	v_exp_f32_e32 v8, v8
	ds_write_b128 v55, v[4:7] offset:18432
	v_add_f32_e32 v15, 1.0, v15
	v_add_f32_e32 v14, 1.0, v14
	v_add_f32_e32 v13, 1.0, v13
	v_add_f32_e32 v26, 1.0, v10
	v_add_f32_e32 v27, 1.0, v9
	v_add_f32_e32 v28, 1.0, v8
	v_rcp_f32_e32 v8, v15
	v_rcp_f32_e32 v9, v14
	v_rcp_f32_e32 v10, v13
	v_rcp_f32_e32 v13, v26
	s_cmp_lg_u64 s[16:17], 0
	s_cbranch_scc1 .Lp7_np
	s_waitcnt vmcnt(18)
	s_branch .Lp7_wd

; #define LAS __attribute__((address_space(3)))
; DI float h2f(unsigned short u) { return (float)__builtin_bit_cast(_Float16, u); }
; DI unsigned pk2(float lo, float hi) { f32x2 v = {lo, hi}; bf2_t b = __builtin_convertvector(v, bf2_t); return __builtin_bit_cast(unsigned, b); }
; DI float fexp(float x) { return __builtin_amdgcn_exp2f(x * 1.4426950408889634f); }
; DI float flog(float x) { return __builtin_amdgcn_logf(x) * 0.6931471805599453f; }
; DI float sigmoidf_(float x) { return frcp(1.f + fexp(-x)); }
; DI void hgA_item(LAS unsigned char* lds, unsigned char* ws, unsigned char* ob, int item, const unsigned (&lfr)[16], const u32x4 (&ivw)[2], const float* lbp) {
;     ...
;     { const float lbk = lbp[h * 128 + (tid & 127)];
; #pragma unroll
;       for (int i = 0; i < 16; ++i) { const float om = (1.f - lbk) * sigmoidf_(-h2f((unsigned short)lfr[i])); kk[i] = om; lf[i] = flog(1.f - om); } }
;     float cs[16]; float run = 0.f;
; #pragma unroll
;     for (int i = 0; i < 16; ++i) { run += lf[i]; cs[i] = run; }
;     tot[tq * 128 + k] = run;
;     hg_iv_store(VTs, ivw);
;     __syncthreads();
;     const float t0s = tot[k], t1s = tot[128 + k], t2s = tot[256 + k], t3s = tot[384 + k];
;     const float off = (tq > 0 ? t0s : 0.f) + (tq > 1 ? t1s : 0.f) + (tq > 2 ? t2s : 0.f);
;     const float blast = (t0s + t1s) + (t2s + t3s);
;     {
;         float kt[16];
; #pragma unroll
;         for (int i = 0; i < 16; ++i) kt[i] = kk[i] * fexp(blast - (off + cs[i]));
;         u32x4 w0, w1;
;         w0.x = pk2(kt[0], kt[1]); w0.y = pk2(kt[2], kt[3]); w0.z = pk2(kt[4], kt[5]); w0.w = pk2(kt[6], kt[7]);
;         w1.x = pk2(kt[8], kt[9]); w1.y = pk2(kt[10], kt[11]); w1.z = pk2(kt[12], kt[13]); w1.w = pk2(kt[14], kt[15]);
;         *(LAS u32x4*)(KTs + k * TROW + tq * 32) = w0; *(LAS u32x4*)(KTs + k * TROW + tq * 32 + 16) = w1;
;     }
;     if (tq == 0) ((float*)(ws + WS_DEC))[(size_t)item * 128 + k] = fexp(blast);
.Lp7_wd:
	v_sub_f32_e32 v24, 1.0, v100
	v_pk_mul_f32 v[4:5], v[22:23], v[24:25] op_sel_hi:[1,0]
	v_pk_mul_f32 v[18:19], v[18:19], v[24:25] op_sel_hi:[1,0]
	v_sub_f32_e32 v6, 1.0, v4
	v_log_f32_e32 v22, v6
	v_sub_f32_e32 v6, 1.0, v5
	v_log_f32_e32 v23, v6
	v_pk_mul_f32 v[6:7], v[20:21], v[24:25] op_sel_hi:[1,0]
	v_sub_f32_e32 v25, 1.0, v18
	v_log_f32_e32 v25, v25
	v_rcp_f32_e32 v14, v27
	v_rcp_f32_e32 v15, v28
	v_sub_f32_e32 v26, 1.0, v19
	v_pk_mul_f32 v[8:9], v[8:9], v[24:25] op_sel_hi:[1,0]
	v_pk_mul_f32 v[16:17], v[16:17], v[24:25] op_sel_hi:[1,0]
	v_pk_mul_f32 v[14:15], v[14:15], v[24:25] op_sel_hi:[1,0]
	v_pk_mul_f32 v[12:13], v[12:13], v[24:25] op_sel_hi:[1,0]
	v_pk_mul_f32 v[10:11], v[10:11], v[24:25] op_sel_hi:[1,0]
	v_sub_f32_e32 v24, 1.0, v8
	v_log_f32_e32 v24, v24
	v_sub_f32_e32 v76, 1.0, v9
	v_sub_f32_e32 v75, 1.0, v10
	v_log_f32_e32 v76, v76
	v_log_f32_e32 v75, v75
	v_sub_f32_e32 v77, 1.0, v11
	v_sub_f32_e32 v31, 1.0, v12
	v_log_f32_e32 v77, v77
	v_log_f32_e32 v31, v31
	v_sub_f32_e32 v40, 1.0, v13
	v_fma_f32 v78, v24, s3, 0
	v_sub_f32_e32 v29, 1.0, v14
	v_log_f32_e32 v40, v40
	v_fmamk_f32 v76, v76, 0x3f317218, v78
	v_log_f32_e32 v29, v29
	v_sub_f32_e32 v30, 1.0, v15
	v_fmamk_f32 v75, v75, 0x3f317218, v76
	v_sub_f32_e32 v27, 1.0, v16
	v_log_f32_e32 v30, v30
	v_fmamk_f32 v77, v77, 0x3f317218, v75
	v_log_f32_e32 v27, v27
	v_sub_f32_e32 v28, 1.0, v17
	v_fmamk_f32 v31, v31, 0x3f317218, v77
	v_log_f32_e32 v28, v28
	v_fmamk_f32 v40, v40, 0x3f317218, v31
	v_fmamk_f32 v29, v29, 0x3f317218, v40
	v_sub_f32_e32 v20, 1.0, v6
	v_log_f32_e32 v26, v26
	v_fmamk_f32 v30, v30, 0x3f317218, v29
	v_log_f32_e32 v20, v20
	v_sub_f32_e32 v21, 1.0, v7
	v_fmamk_f32 v79, v27, 0x3f317218, v30
	v_log_f32_e32 v21, v21
	v_fmamk_f32 v28, v28, 0x3f317218, v79
	v_fmamk_f32 v80, v25, 0x3f317218, v28
	v_fmamk_f32 v81, v26, 0x3f317218, v80
	v_fmamk_f32 v82, v20, 0x3f317218, v81
	v_fmamk_f32 v83, v21, 0x3f317218, v82
	v_fmamk_f32 v84, v22, 0x3f317218, v83
	v_fmamk_f32 v21, v23, 0x3f317218, v84
	ds_write_b32 v52, v21 offset:36864
	ds_write_b128 v56, v[0:3] offset:18432
	s_waitcnt lgkmcnt(0)
	s_barrier
	ds_read2st64_b32 v[0:1], v53 offset0:144 offset1:146
	ds_read2st64_b32 v[2:3], v53 offset0:148 offset1:150
	v_readfirstlane_b32 s38, v253
	s_waitcnt lgkmcnt(1)
	v_cndmask_b32_e64 v20, v0, 0, s[4:5]
	v_cndmask_b32_e64 v22, 0, v1, s[6:7]
	v_add_f32_e32 v23, v20, v22
	s_waitcnt lgkmcnt(0)
	v_cndmask_b32_e64 v25, 0, v2, s[8:9]
	v_mov_b32_e32 v22, v0
	v_mov_b32_e32 v24, v1
	v_pk_add_f32 v[22:23], v[22:23], v[24:25]
	v_add_f32_e32 v20, v2, v3
	v_pk_add_f32 v[0:1], v[22:23], v[20:21]
	v_add_f32_e32 v22, v31, v23
	v_sub_f32_e32 v22, v0, v22
	v_mul_f32_e32 v22, 0x3fb8aa3b, v22
	v_exp_f32_e32 v24, v22
	v_add_f32_e32 v22, v23, v40
	v_sub_f32_e32 v22, v0, v22
	v_mul_f32_e32 v22, 0x3fb8aa3b, v22
	v_exp_f32_e32 v25, v22
	v_add_f32_e32 v22, v23, v29
	v_sub_f32_e32 v22, v0, v22
	v_add_f32_e32 v2, v78, v23
	v_add_f32_e32 v3, v76, v23
	v_add_f32_e32 v20, v75, v23
	v_add_f32_e32 v21, v77, v23
	v_mul_f32_e32 v22, 0x3fb8aa3b, v22
	v_sub_f32_e32 v2, v0, v2
	v_sub_f32_e32 v3, v0, v3
	v_sub_f32_e32 v20, v0, v20
	v_sub_f32_e32 v21, v0, v21
	v_exp_f32_e32 v26, v22
	v_add_f32_e32 v22, v23, v30
	v_mul_f32_e32 v2, 0x3fb8aa3b, v2
	v_mul_f32_e32 v3, 0x3fb8aa3b, v3
	v_mul_f32_e32 v20, 0x3fb8aa3b, v20
	v_mul_f32_e32 v21, 0x3fb8aa3b, v21
	v_sub_f32_e32 v22, v0, v22
	v_exp_f32_e32 v2, v2
	v_exp_f32_e32 v3, v3
	v_exp_f32_e32 v20, v20
	v_exp_f32_e32 v21, v21
	v_mul_f32_e32 v22, 0x3fb8aa3b, v22
	v_exp_f32_e32 v27, v22
	v_add_f32_e32 v22, v23, v82
	v_sub_f32_e32 v22, v0, v22
	v_mul_f32_e32 v22, 0x3fb8aa3b, v22
	v_pk_mul_f32 v[2:3], v[8:9], v[2:3]
	v_pk_mul_f32 v[8:9], v[10:11], v[20:21]
	v_pk_mul_f32 v[10:11], v[12:13], v[24:25]
	v_exp_f32_e32 v24, v22
	v_add_f32_e32 v22, v23, v83
	v_sub_f32_e32 v22, v0, v22
	v_mul_f32_e32 v22, 0x3fb8aa3b, v22
	v_pk_mul_f32 v[12:13], v[14:15], v[26:27]
	v_add_f32_e32 v14, v23, v79
	v_add_f32_e32 v15, v23, v28
	v_add_f32_e32 v20, v23, v80
	v_add_f32_e32 v21, v23, v81
	v_exp_f32_e32 v25, v22
	v_add_f32_e32 v22, v23, v84
	v_sub_f32_e32 v14, v0, v14
	v_sub_f32_e32 v15, v0, v15
	v_sub_f32_e32 v20, v0, v20
	v_sub_f32_e32 v21, v0, v21
	v_sub_f32_e32 v22, v0, v22
	v_sub_f32_e32 v1, v0, v1
	v_mul_f32_e32 v14, 0x3fb8aa3b, v14
	v_mul_f32_e32 v15, 0x3fb8aa3b, v15
	v_mul_f32_e32 v20, 0x3fb8aa3b, v20
	v_mul_f32_e32 v21, 0x3fb8aa3b, v21
	v_mul_f32_e32 v22, 0x3fb8aa3b, v22
	v_mul_f32_e32 v1, 0x3fb8aa3b, v1
	v_exp_f32_e32 v14, v14
	v_exp_f32_e32 v15, v15
	v_exp_f32_e32 v20, v20
	v_exp_f32_e32 v21, v21
	v_exp_f32_e32 v22, v22
	v_exp_f32_e32 v23, v1
	v_pk_mul_f32 v[14:15], v[16:17], v[14:15]
	v_pk_mul_f32 v[16:17], v[18:19], v[20:21]
	v_pk_mul_f32 v[18:19], v[6:7], v[24:25]
	v_pk_mul_f32 v[20:21], v[4:5], v[22:23]
	v_cvt_pk_bf16_f32 v2, v2, v3
	v_cvt_pk_bf16_f32 v3, v8, v9
	v_cvt_pk_bf16_f32 v4, v10, v11
	v_cvt_pk_bf16_f32 v5, v12, v13
	v_cvt_pk_bf16_f32 v6, v14, v15
	v_cvt_pk_bf16_f32 v7, v16, v17
	v_cvt_pk_bf16_f32 v8, v18, v19
	v_cvt_pk_bf16_f32 v9, v20, v21
	ds_write_b128 v57, v[2:5]
	ds_write_b128 v57, v[6:9] offset:16
	s_and_saveexec_b64 s[18:19], s[4:5]
	s_cbranch_execz .LBB0_988
	v_mul_f32_e32 v0, 0x3fb8aa3b, v0
	v_exp_f32_e32 v0, v0
	global_store_dword v[50:51], v0, off
	s_branch .LBB0_988

; #define LAS __attribute__((address_space(3)))
; DI float siluf_(float x) { return x * frcp(1.f + fexp(-x)); }
; DI u32x4 pack8(const f32x4 a, const f32x4 b) { u32x4 w; w.x = pk2(a[0], a[1]); w.y = pk2(a[2], a[3]); w.z = pk2(b[0], b[1]); w.w = pk2(b[2], b[3]); return w; }
; DI void hgC_item(LAS unsigned char* lds, unsigned char* ws, unsigned char* ob, int item, const float* ng, int dummy, const unsigned (&lfr)[16], const unsigned (&qvr)[16], const u32x4 (&ivw)[2], const float* lbp) {
;     ...
;     float ss = 0.f;
; #pragma unroll
;     for (int i = 0; i < 16; ++i) ss += acc[i] * acc[i];
;     ss += __shfl_xor(ss, 32);
;     if (h2 == 0) red[vb * 64 + tb * 32 + r] = ss;
;     __syncthreads();
;     {
;         const int t = tb * 32 + r;
;         const float tots = (red[t] + red[64 + t]) + (red[128 + t] + red[192 + t]);
;         const float rs = rsqrtf(tots * (1.f / 128.f) + EPS_);
;         LAS unsigned char* OB = QI;
; #pragma unroll
;         for (int g4 = 0; g4 < 4; ++g4) {
;             const int v0 = 32 * vb + 8 * g4 + 4 * h2;
;             const f32x4 o = {acc[4 * g4 + 0] * rs, acc[4 * g4 + 1] * rs, acc[4 * g4 + 2] * rs, acc[4 * g4 + 3] * rs};
;             *(LAS u32x2*)(OB + t * HROW + v0 * 2) = pack4(o);
;         }
;     }
;     __syncthreads();
; #pragma unroll
;     for (int j = 0; j < 2; ++j) {
;         const int id = tid + 512 * j, t = id >> 4, c8 = (id & 15) * 8;
;         const u32x4 ov = *(const LAS u32x4*)(QI + t * HROW + c8 * 2);
;         const f32x4 n0 = *(const f32x4*)(ng + c8), n1 = *(const f32x4*)(ng + c8 + 4);
;         const u32x4 z = gz[j];
;         f32x4 o0, o1;
;         o0[0] = bflo(ov.x) * n0[0] * siluf_(bflo(z.x)); o0[1] = bfhi(ov.x) * n0[1] * siluf_(bfhi(z.x));
;         o0[2] = bflo(ov.y) * n0[2] * siluf_(bflo(z.y)); o0[3] = bfhi(ov.y) * n0[3] * siluf_(bfhi(z.y));
;         o1[0] = bflo(ov.z) * n1[0] * siluf_(bflo(z.z)); o1[1] = bfhi(ov.z) * n1[1] * siluf_(bfhi(z.z));
;         o1[2] = bflo(ov.w) * n1[2] * siluf_(bflo(z.w)); o1[3] = bfhi(ov.w) * n1[3] * siluf_(bfhi(z.w));
;         *(u32x4*)(MIX2 + (size_t)(t0 + t) * DM + h * 128 + c8) = pack8(o0, o1);
;     }
;     __syncthreads();
; __global__ void __launch_bounds__(512, 2) fwd_kernel(Args a) {
;     ...
; #pragma unroll
;             for (int i = 0; i < 16; ++i) { lfa[i] = lfb[i]; qva[i] = qvb[i]; }
;             iva[0] = ivb[0]; iva[1] = ivb[1]; it = nx;
;         }
.LBB0_1111:
	s_waitcnt vmcnt(0)
	s_or_b64 exec, exec, s[90:91]
	v_lshl_add_u32 v16, v136, 2, 0
	v_add_u32_e32 v18, 0x12400, v16
	s_waitcnt lgkmcnt(0)
	s_barrier
	ds_read2st64_b32 v[16:17], v18 offset1:1
	ds_read2st64_b32 v[18:19], v18 offset0:2 offset1:3
	s_mov_b32 s33, 0x800000
	v_add_u32_e32 v28, v112, v107
	v_mov_b32_e32 v50, v134
	s_waitcnt lgkmcnt(1)
	v_mov_b32_e32 v20, v16
	s_waitcnt lgkmcnt(0)
	v_mov_b32_e32 v21, v18
	v_mov_b32_e32 v18, v17
	v_pk_add_f32 v[16:17], v[20:21], v[18:19]
	v_lshlrev_b32_e32 v18, 16, v47
	v_add_f32_e32 v16, v16, v17
	v_fmamk_f32 v16, v16, 0x3c000000, v119
	v_mul_f32_e32 v17, 0x4b800000, v16
	v_cmp_gt_f32_e32 vcc, s33, v16
	s_lshl_b32 s33, s75, 6
	v_and_b32_e32 v19, 0xffff0000, v47
	v_cndmask_b32_e32 v16, v16, v17, vcc
	v_rsq_f32_e32 v16, v16
	v_mul_f32_e32 v23, 0xbfb8aa3b, v18
	v_mul_f32_e32 v24, 0xbfb8aa3b, v19
	v_exp_f32_e32 v30, v23
	v_mul_f32_e32 v17, 0x45800000, v16
	v_cndmask_b32_e32 v16, v16, v17, vcc
	v_add3_u32 v17, v93, s33, v110
	v_pk_mul_f32 v[0:1], v[0:1], v[16:17] op_sel_hi:[1,0]
	v_pk_mul_f32 v[2:3], v[2:3], v[16:17] op_sel_hi:[1,0]
	v_cvt_pk_bf16_f32 v0, v0, v1
	v_cvt_pk_bf16_f32 v1, v2, v3
	v_pk_mul_f32 v[2:3], v[4:5], v[16:17] op_sel_hi:[1,0]
	v_pk_mul_f32 v[4:5], v[6:7], v[16:17] op_sel_hi:[1,0]
	v_cvt_pk_bf16_f32 v2, v2, v3
	v_cvt_pk_bf16_f32 v3, v4, v5
	ds_write2_b64 v17, v[0:1], v[2:3] offset1:2
	v_pk_mul_f32 v[0:1], v[8:9], v[16:17] op_sel_hi:[1,0]
	v_pk_mul_f32 v[2:3], v[10:11], v[16:17] op_sel_hi:[1,0]
	v_cvt_pk_bf16_f32 v0, v0, v1
	v_cvt_pk_bf16_f32 v1, v2, v3
	v_pk_mul_f32 v[2:3], v[12:13], v[16:17] op_sel_hi:[1,0]
	v_pk_mul_f32 v[4:5], v[14:15], v[16:17] op_sel_hi:[1,0]
	v_cvt_pk_bf16_f32 v2, v2, v3
	v_cvt_pk_bf16_f32 v3, v4, v5
	ds_write2_b64 v17, v[0:1], v[2:3] offset0:4 offset1:6
	s_waitcnt lgkmcnt(0)
	s_barrier
	global_load_dwordx4 v[0:3], v[90:91], off
	global_load_dwordx4 v[4:7], v[90:91], off offset:16
	v_lshlrev_b32_e32 v12, 16, v44
	v_and_b32_e32 v13, 0xffff0000, v44
	v_lshlrev_b32_e32 v14, 16, v45
	v_lshlrev_b32_e32 v16, 16, v46
	v_and_b32_e32 v17, 0xffff0000, v46
	v_mul_f32_e32 v9, 0xbfb8aa3b, v12
	v_mul_f32_e32 v10, 0xbfb8aa3b, v13
	v_mul_f32_e32 v11, 0xbfb8aa3b, v14
	v_mul_f32_e32 v21, 0xbfb8aa3b, v16
	v_mul_f32_e32 v22, 0xbfb8aa3b, v17
	v_exp_f32_e32 v9, v9
	v_exp_f32_e32 v10, v10
	v_exp_f32_e32 v11, v11
	v_exp_f32_e32 v26, v21
	v_exp_f32_e32 v22, v22
	v_add_u32_e32 v8, v112, v106
	v_and_b32_e32 v15, 0xffff0000, v45
	v_add_f32_e32 v9, 1.0, v9
	v_add_f32_e32 v10, 1.0, v10
	v_add_f32_e32 v11, 1.0, v11
	v_mul_f32_e32 v20, 0xbfb8aa3b, v15
	v_exp_f32_e32 v31, v24
	v_add_f32_e32 v26, 1.0, v26
	v_add_f32_e32 v27, 1.0, v22
	v_rcp_f32_e32 v22, v9
	v_rcp_f32_e32 v23, v10
	v_rcp_f32_e32 v24, v11
	ds_read_b128 v[8:11], v8
	v_exp_f32_e32 v25, v20
	v_rcp_f32_e32 v26, v26
	v_rcp_f32_e32 v27, v27
	s_lshl_b32 s33, s97, 1
	v_add_f32_e32 v25, 1.0, v25
	v_rcp_f32_e32 v25, v25
	v_pk_mul_f32 v[16:17], v[26:27], v[16:17]
	s_waitcnt lgkmcnt(0)
	v_lshlrev_b32_e32 v26, 16, v8
	v_and_b32_e32 v27, 0xffff0000, v8
	v_lshlrev_b32_e32 v8, 16, v9
	v_and_b32_e32 v9, 0xffff0000, v9
	s_add_u32 s56, s86, s33
	v_pk_mul_f32 v[22:23], v[22:23], v[12:13]
	v_pk_mul_f32 v[24:25], v[24:25], v[14:15]
	ds_read_b128 v[12:15], v28
	v_lshlrev_b32_e32 v28, 16, v10
	v_and_b32_e32 v29, 0xffff0000, v10
	v_lshlrev_b32_e32 v10, 16, v11
	v_and_b32_e32 v11, 0xffff0000, v11
	v_mov_b32_e32 v93, v81
	s_addc_u32 s57, s87, 0
	v_lshl_add_u64 v[20:21], s[56:57], 0, v[92:93]
	s_andn2_b64 vcc, exec, s[76:77]
	v_mov_b32_e32 v52, v130
	v_mov_b32_e32 v56, v128
	v_mov_b32_e32 v48, v120
	v_mov_b32_e32 v70, v135
	v_mov_b32_e32 v71, v133
	v_mov_b32_e32 v51, v131
	v_mov_b32_e32 v53, v129
	s_mov_b32 s68, s74
	s_waitcnt vmcnt(1)
	v_pk_mul_f32 v[2:3], v[2:3], v[8:9]
	v_add_f32_e32 v8, 1.0, v30
	v_add_f32_e32 v9, 1.0, v31
	v_rcp_f32_e32 v8, v8
	v_rcp_f32_e32 v9, v9
	v_pk_mul_f32 v[0:1], v[0:1], v[26:27]
	s_waitcnt vmcnt(0)
	v_pk_mul_f32 v[4:5], v[4:5], v[28:29]
	v_pk_mul_f32 v[6:7], v[6:7], v[10:11]
	v_pk_mul_f32 v[8:9], v[8:9], v[18:19]
	v_pk_mul_f32 v[0:1], v[22:23], v[0:1]
	v_pk_mul_f32 v[2:3], v[24:25], v[2:3]
	v_pk_mul_f32 v[4:5], v[16:17], v[4:5]
	v_pk_mul_f32 v[6:7], v[8:9], v[6:7]
	v_cvt_pk_bf16_f32 v0, v0, v1
	v_cvt_pk_bf16_f32 v1, v2, v3
	v_cvt_pk_bf16_f32 v2, v4, v5
	v_cvt_pk_bf16_f32 v3, v6, v7
	v_lshl_add_u64 v[4:5], v[20:21], 0, v[96:97]
	global_store_dwordx4 v[4:5], v[0:3], off
	global_load_dwordx4 v[0:3], v[90:91], off
	s_nop 0
	global_load_dwordx4 v[4:7], v[90:91], off offset:16
	v_lshlrev_b32_e32 v8, 16, v40
	v_and_b32_e32 v9, 0xffff0000, v40
	v_lshlrev_b32_e32 v10, 16, v41
	v_and_b32_e32 v11, 0xffff0000, v41
	v_lshlrev_b32_e32 v16, 16, v42
	v_and_b32_e32 v17, 0xffff0000, v42
	v_lshlrev_b32_e32 v18, 16, v43
	v_and_b32_e32 v19, 0xffff0000, v43
	v_mul_f32_e32 v22, 0xbfb8aa3b, v8
	v_mul_f32_e32 v23, 0xbfb8aa3b, v9
	v_mul_f32_e32 v24, 0xbfb8aa3b, v10
	v_mul_f32_e32 v25, 0xbfb8aa3b, v11
	v_mul_f32_e32 v26, 0xbfb8aa3b, v16
	v_mul_f32_e32 v27, 0xbfb8aa3b, v17
	v_mul_f32_e32 v28, 0xbfb8aa3b, v18
	v_mul_f32_e32 v29, 0xbfb8aa3b, v19
	v_exp_f32_e32 v22, v22
	v_exp_f32_e32 v23, v23
	v_exp_f32_e32 v24, v24
	v_exp_f32_e32 v25, v25
	v_exp_f32_e32 v26, v26
	v_exp_f32_e32 v27, v27
	v_exp_f32_e32 v28, v28
	v_exp_f32_e32 v29, v29
	v_add_f32_e32 v22, 1.0, v22
	v_add_f32_e32 v23, 1.0, v23
	v_add_f32_e32 v24, 1.0, v24
	v_add_f32_e32 v25, 1.0, v25
	v_add_f32_e32 v26, 1.0, v26
	v_add_f32_e32 v27, 1.0, v27
	v_add_f32_e32 v28, 1.0, v28
	v_add_f32_e32 v29, 1.0, v29
	v_rcp_f32_e32 v22, v22
	v_rcp_f32_e32 v23, v23
	v_rcp_f32_e32 v24, v24
	v_rcp_f32_e32 v25, v25
	v_rcp_f32_e32 v26, v26
	v_rcp_f32_e32 v27, v27
	v_rcp_f32_e32 v28, v28
	v_rcp_f32_e32 v29, v29
	v_pk_mul_f32 v[8:9], v[22:23], v[8:9]
	v_pk_mul_f32 v[10:11], v[24:25], v[10:11]
	s_waitcnt lgkmcnt(0)
	v_lshlrev_b32_e32 v22, 16, v12
	v_and_b32_e32 v23, 0xffff0000, v12
	v_lshlrev_b32_e32 v12, 16, v13
	v_and_b32_e32 v13, 0xffff0000, v13
	v_lshlrev_b32_e32 v24, 16, v14
	v_and_b32_e32 v25, 0xffff0000, v14
	v_lshlrev_b32_e32 v14, 16, v15
	v_and_b32_e32 v15, 0xffff0000, v15
	v_pk_mul_f32 v[16:17], v[26:27], v[16:17]
	v_pk_mul_f32 v[18:19], v[28:29], v[18:19]
	v_lshl_add_u64 v[20:21], v[20:21], 0, v[94:95]
	v_mov_b32_e32 v26, v126
	v_mov_b32_e32 v28, v124
	v_mov_b32_e32 v30, v122
	v_mov_b32_e32 v27, v125
	v_mov_b32_e32 v29, v123
	v_mov_b32_e32 v31, v121
	s_waitcnt vmcnt(1)
	v_pk_mul_f32 v[0:1], v[0:1], v[22:23]
	v_pk_mul_f32 v[2:3], v[2:3], v[12:13]
	s_waitcnt vmcnt(0)
	v_pk_mul_f32 v[4:5], v[4:5], v[24:25]
	v_pk_mul_f32 v[6:7], v[6:7], v[14:15]
	v_pk_mul_f32 v[0:1], v[8:9], v[0:1]
	v_pk_mul_f32 v[2:3], v[10:11], v[2:3]
	v_pk_mul_f32 v[4:5], v[16:17], v[4:5]
	v_pk_mul_f32 v[6:7], v[18:19], v[6:7]
	v_cvt_pk_bf16_f32 v0, v0, v1
	v_cvt_pk_bf16_f32 v1, v2, v3
	v_cvt_pk_bf16_f32 v2, v4, v5
	v_cvt_pk_bf16_f32 v3, v6, v7
	global_store_dwordx4 v[20:21], v[0:3], off
	v_mov_b64_e32 v[4:5], v[32:33]
	v_mov_b32_e32 v25, v132
	v_mov_b64_e32 v[0:1], v[36:37]
	v_mov_b32_e32 v24, v127
	v_mov_b64_e32 v[6:7], v[34:35]
	v_mov_b64_e32 v[2:3], v[38:39]
	s_barrier
	s_cbranch_vccz .LBB0_1124
; DI bf16_t* ds_item_ptr(unsigned char* ws, unsigned char* ob, int b, int h, int c) { return (bf16_t*)(b == 0 ? ws + WS_DS0 : ob) + ((size_t)(h * 64 + c)) * 16384; }
; DI void hgC_load(unsigned char* ws, int item, unsigned (&lf)[16], unsigned (&qv)[16], u32x4 (&ivw)[2]) {
;     const int tid = threadIdx.x, b = item >> 10, h = (item >> 6) & 15, c = item & 63, t0 = b * SEQ + c * 64, kp = tid & 63, tq = tid >> 6;
;     const bf16_t* LOGF = (const bf16_t*)(ws + WS_LOGF);
;     const bf16_t* Q2 = (const bf16_t*)(ws + WS_Q2);
; #pragma unroll
;     for (int i = 0; i < 8; ++i) { const size_t o = (size_t)(t0 + tq * 8 + i) * DM + h * 128 + 2 * kp; lf[i] = *(const unsigned*)(LOGF + o); qv[i] = *(const unsigned*)(Q2 + o); }
;     hg_iv_load((const bf16_t*)(ws + WS_IV), item, ivw);
; DI void hgC_item(LAS unsigned char* lds, unsigned char* ws, unsigned char* ob, int item, const float* ng, int dummy, const unsigned (&lfr)[16], const unsigned (&qvr)[16], const u32x4 (&ivw)[2], const float* lbp) {
;     ...
;     u32x4 sreg[4], gz[2];
;     { const bf16_t* Sg = ds_item_ptr(ws, ob, b, h, c);
; #pragma unroll
;       for (int j = 0; j < 4; ++j) sreg[j] = *(const u32x4*)(Sg + (size_t)(tid + 512 * j) * 8);
; #pragma unroll
;       for (int j = 0; j < 2; ++j) { const int id = tid + 512 * j; gz[j] = *(const u32x4*)(G2 + (size_t)(t0 + (id >> 4)) * DM + h * 128 + (id & 15) * 8); } }
;     float kk0[8], kk1[8], q0v[8], q1v[8], cs0[8], cs1[8];
;     {
;         const f32x2 lb2 = *(const f32x2*)(lbp + h * 128 + 2 * kp);
.LBB0_1112:
	s_add_i32 s74, s68, s58
	s_cmpk_gt_i32 s74, 0x7ff
	s_cselect_b64 s[76:77], -1, 0
	s_and_b64 vcc, exec, s[76:77]
	v_mov_b32_e32 v134, 0
	v_mov_b32_e32 v132, 0
	v_mov_b32_e32 v130, 0
	v_mov_b32_e32 v128, 0
	v_mov_b32_e32 v126, 0
	v_mov_b32_e32 v124, 0
	v_mov_b32_e32 v122, 0
	v_mov_b32_e32 v120, 0
	v_mov_b32_e32 v135, 0
	v_mov_b32_e32 v133, 0
	v_mov_b32_e32 v131, 0
	v_mov_b32_e32 v129, 0
	v_mov_b32_e32 v127, 0
	v_mov_b32_e32 v125, 0
	v_mov_b32_e32 v123, 0
	v_mov_b32_e32 v121, 0
	s_lshl_b32 s56, s68, 2
	v_readfirstlane_b32 s97, v99
	s_and_b32 s90, s56, 0xfffff000
	s_andn2_b64 vcc, exec, s[70:71]
	s_mov_b64 s[86:87], s[66:67]
	s_cbranch_vccnz .LBB0_1116
	s_ashr_i32 s91, s90, 31
	s_lshl_b64 s[56:57], s[90:91], 12
	s_sub_u32 s56, 0, s56
	s_subb_u32 s57, 0, s57
	s_add_u32 s86, s73, s56
	s_addc_u32 s87, s93, s57
.LBB0_1116:
	s_and_b32 s56, s68, 63
	s_lshl_b32 s57, s56, 6
	s_bfe_u32 s91, s68, 0x40006
	s_or_b32 s33, s90, s57
	s_and_b32 s75, s97, 3
	s_cmpk_lt_u32 s68, 0x400
	s_cselect_b32 s57, s95, s81
	s_cselect_b32 s68, s94, s80
	s_lshl_b32 s56, s56, 15
	s_lshl_b32 s90, s91, 21
	s_or_b32 s56, s90, s56
	s_add_u32 s56, s68, s56
	s_addc_u32 s57, s57, 0
	v_lshl_add_u64 v[20:21], s[56:57], 0, v[80:81]
	v_add_co_u32_e32 v12, vcc, s3, v20
	global_load_dwordx4 v[8:11], v80, s[56:57]
	s_nop 0
	v_addc_co_u32_e32 v13, vcc, 0, v21, vcc
	s_movk_i32 s56, 0x4000
	v_add_co_u32_e32 v16, vcc, s56, v20
	v_or_b32_e32 v42, s33, v101
	v_add_u32_e32 v44, s33, v102
	v_addc_co_u32_e32 v17, vcc, 0, v21, vcc
	s_movk_i32 s56, 0x6000
	s_lshl_b32 s68, s91, 8
	v_ashrrev_i32_e32 v43, 31, v42
	v_ashrrev_i32_e32 v45, 31, v44
	v_add_co_u32_e32 v20, vcc, s56, v20
	v_lshl_add_u64 v[40:41], v[84:85], 0, s[68:69]
	v_lshlrev_b64 v[96:97], 12, v[42:43]
	v_lshlrev_b64 v[94:95], 12, v[44:45]
	s_lshl_b32 s68, s91, 9
	v_addc_co_u32_e32 v21, vcc, 0, v21, vcc
	v_lshl_add_u64 v[42:43], v[40:41], 0, v[96:97]
	v_lshl_add_u64 v[40:41], v[40:41], 0, v[94:95]
	v_cvt_f32_f16_e32 v54, v48
	v_cvt_f32_f16_sdwa v55, v48 dst_sel:DWORD dst_unused:UNUSED_PAD src0_sel:WORD_1
	v_lshl_add_u64 v[48:49], v[86:87], 0, s[68:69]
	global_load_dwordx4 v[12:15], v[12:13], off
	s_nop 0
	global_load_dwordx4 v[16:19], v[16:17], off
	v_mul_f32_e32 v54, 0x3fb8aa3b, v54
	global_load_dwordx4 v[20:23], v[20:21], off
	s_nop 0
	global_load_dwordx4 v[44:47], v[42:43], off
	s_nop 0
	global_load_dwordx4 v[40:43], v[40:41], off
	v_exp_f32_e32 v54, v54
	global_load_dwordx2 v[58:59], v[48:49], off
	s_and_b64 vcc, exec, s[76:77]
	s_cbranch_vccnz .LBB0_1114
	s_lshl_b32 s56, s74, 2
	s_lshl_b32 s57, s74, 6
	s_and_b32 s56, s56, 0xfffff000
	s_and_b32 s57, s57, 0xfc0
	s_or_b32 s56, s56, s57
	v_add_u32_e32 v148, s56, v89
	s_lshl_b32 s56, s74, 1
	s_and_b32 s56, s56, 0x780
	v_or_b32_e32 v152, s56, v98
	v_ashrrev_i32_e32 v149, 31, v148
	v_or_b32_e32 v154, 1, v148
	v_or_b32_e32 v158, 2, v148
	v_or_b32_e32 v162, 3, v148
	v_lshlrev_b64 v[150:151], 12, v[148:149]
	v_lshlrev_b32_e32 v34, 1, v152
	v_ashrrev_i32_e32 v155, 31, v154
	v_ashrrev_i32_e32 v159, 31, v158
	v_ashrrev_i32_e32 v163, 31, v162
	v_or_b32_e32 v150, v150, v34
	v_lshlrev_b64 v[154:155], 12, v[154:155]
	v_lshlrev_b64 v[158:159], 12, v[158:159]
	v_lshlrev_b64 v[162:163], 12, v[162:163]
	v_lshl_add_u64 v[152:153], s[64:65], 0, v[150:151]
	v_lshl_add_u64 v[150:151], s[66:67], 0, v[150:151]
	v_or_b32_e32 v154, v154, v34
	v_or_b32_e32 v158, v158, v34
	v_or_b32_e32 v162, v162, v34
	v_lshl_add_u64 v[156:157], s[64:65], 0, v[154:155]
	v_lshl_add_u64 v[154:155], s[66:67], 0, v[154:155]
	v_lshl_add_u64 v[160:161], s[64:65], 0, v[158:159]
	v_lshl_add_u64 v[158:159], s[66:67], 0, v[158:159]
	v_lshl_add_u64 v[32:33], s[64:65], 0, v[162:163]
	v_lshl_add_u64 v[162:163], s[66:67], 0, v[162:163]
	global_load_dword v120, v[152:153], off
	global_load_dword v121, v[150:151], off
	global_load_dword v122, v[156:157], off
	global_load_dword v123, v[154:155], off
	global_load_dword v124, v[160:161], off
	global_load_dword v125, v[158:159], off
	global_load_dword v126, v[32:33], off
	global_load_dword v127, v[162:163], off
	v_or_b32_e32 v150, 4, v148
	v_ashrrev_i32_e32 v151, 31, v150
	v_or_b32_e32 v154, 5, v148
	v_or_b32_e32 v158, 6, v148
	v_or_b32_e32 v148, 7, v148
	v_lshlrev_b64 v[150:151], 12, v[150:151]
	v_ashrrev_i32_e32 v155, 31, v154
	v_ashrrev_i32_e32 v159, 31, v158
	v_ashrrev_i32_e32 v149, 31, v148
	v_or_b32_e32 v150, v150, v34
	v_lshlrev_b64 v[154:155], 12, v[154:155]
	v_lshlrev_b64 v[158:159], 12, v[158:159]
	v_lshlrev_b64 v[148:149], 12, v[148:149]
	v_lshl_add_u64 v[152:153], s[64:65], 0, v[150:151]
	v_or_b32_e32 v154, v154, v34
	v_or_b32_e32 v158, v158, v34
	v_or_b32_e32 v148, v148, v34
	v_lshl_add_u64 v[150:151], s[66:67], 0, v[150:151]
	v_lshl_add_u64 v[156:157], s[64:65], 0, v[154:155]
	v_lshl_add_u64 v[154:155], s[66:67], 0, v[154:155]
	v_lshl_add_u64 v[160:161], s[64:65], 0, v[158:159]
	v_lshl_add_u64 v[158:159], s[66:67], 0, v[158:159]
	v_lshl_add_u64 v[162:163], s[64:65], 0, v[148:149]
	v_lshl_add_u64 v[148:149], s[66:67], 0, v[148:149]
	global_load_dword v128, v[152:153], off
	global_load_dword v129, v[150:151], off
	global_load_dword v130, v[156:157], off
	global_load_dword v131, v[154:155], off
	global_load_dword v132, v[160:161], off
	global_load_dword v133, v[158:159], off
	global_load_dword v134, v[162:163], off
	global_load_dword v135, v[148:149], off
	s_mov_b32 s98, s74
	s_ashr_i32 s99, s74, 31
	s_lshl_b64 s[56:57], s[98:99], 14
	v_lshl_add_u64 v[148:149], v[82:83], 0, s[56:57]
	v_add_co_u32_e32 v150, vcc, 0x2000, v148
	s_nop 1
	v_addc_co_u32_e32 v151, vcc, 0, v149, vcc
	global_load_dwordx4 v[32:35], v[148:149], off
	global_load_dwordx4 v[36:39], v[150:151], off
; #define LAS __attribute__((address_space(3)))
; DI float h2f(unsigned short u) { return (float)__builtin_bit_cast(_Float16, u); }
; DI float flog(float x) { return __builtin_amdgcn_logf(x) * 0.6931471805599453f; }
; DI float sigmoidf_(float x) { return frcp(1.f + fexp(-x)); }
; DI void hgC_item(LAS unsigned char* lds, unsigned char* ws, unsigned char* ob, int item, const float* ng, int dummy, const unsigned (&lfr)[16], const unsigned (&qvr)[16], const u32x4 (&ivw)[2], const float* lbp) {
;     ...
;         const f32x2 lb2 = *(const f32x2*)(lbp + h * 128 + 2 * kp);
;         float run0 = 0.f, run1 = 0.f;
; #pragma unroll
;         for (int i = 0; i < 8; ++i) {
;             const float om0 = (1.f - lb2[0]) * sigmoidf_(-h2f((unsigned short)(lfr[i] & 0xffffu)));
;             const float om1 = (1.f - lb2[1]) * sigmoidf_(-h2f((unsigned short)(lfr[i] >> 16)));
;             kk0[i] = om0; kk1[i] = om1;
;             run0 += flog(1.f - om0); run1 += flog(1.f - om1);
;             cs0[i] = run0; cs1[i] = run1;
;             q0v[i] = bflo(qvr[i]); q1v[i] = bfhi(qvr[i]);
;         }
;         *(LAS f32x2*)(tot + tq * 128 + 2 * kp) = (f32x2){run0, run1};
;     }
;     hg_iv_store(VTs, ivw);
.LBB0_1114:
	v_mul_f32_e32 v55, 0x3fb8aa3b, v55
	v_exp_f32_e32 v55, v55
	v_cvt_f32_f16_e32 v49, v30
	v_add_f32_e32 v48, 1.0, v54
	v_rcp_f32_e32 v60, v48
	v_add_f32_e32 v48, 1.0, v55
	v_rcp_f32_e32 v61, v48
	v_cvt_f32_f16_sdwa v30, v30 dst_sel:DWORD dst_unused:UNUSED_PAD src0_sel:WORD_1
	v_mul_f32_e32 v48, 0x3fb8aa3b, v49
	v_exp_f32_e32 v48, v48
	v_lshlrev_b32_e32 v54, 16, v31
	v_mul_f32_e32 v30, 0x3fb8aa3b, v30
	v_exp_f32_e32 v30, v30
	v_and_b32_e32 v55, 0xffff0000, v31
	v_add_f32_e32 v31, 1.0, v48
	v_rcp_f32_e32 v62, v31
	v_cvt_f32_f16_e32 v31, v28
	v_add_f32_e32 v30, 1.0, v30
	v_rcp_f32_e32 v63, v30
	v_cvt_f32_f16_sdwa v28, v28 dst_sel:DWORD dst_unused:UNUSED_PAD src0_sel:WORD_1
	v_mul_f32_e32 v30, 0x3fb8aa3b, v31
	v_exp_f32_e32 v30, v30
	v_lshlrev_b32_e32 v48, 16, v29
	v_mul_f32_e32 v28, 0x3fb8aa3b, v28
	v_exp_f32_e32 v28, v28
	v_and_b32_e32 v49, 0xffff0000, v29
	v_add_f32_e32 v29, 1.0, v30
	v_rcp_f32_e32 v64, v29
	v_cvt_f32_f16_e32 v29, v26
	v_cvt_f32_f16_sdwa v26, v26 dst_sel:DWORD dst_unused:UNUSED_PAD src0_sel:WORD_1
	v_add_f32_e32 v28, 1.0, v28
	v_rcp_f32_e32 v65, v28
	v_mul_f32_e32 v28, 0x3fb8aa3b, v29
	v_exp_f32_e32 v28, v28
	v_mul_f32_e32 v26, 0x3fb8aa3b, v26
	v_exp_f32_e32 v26, v26
	v_lshlrev_b32_e32 v30, 16, v27
	v_and_b32_e32 v31, 0xffff0000, v27
	v_add_f32_e32 v27, 1.0, v28
	v_rcp_f32_e32 v66, v27
	v_add_f32_e32 v26, 1.0, v26
	v_cvt_f32_f16_e32 v27, v56
	v_rcp_f32_e32 v67, v26
	v_cvt_f32_f16_sdwa v26, v56 dst_sel:DWORD dst_unused:UNUSED_PAD src0_sel:WORD_1
	v_lshlrev_b32_e32 v28, 16, v24
	v_mul_f32_e32 v27, 0x3fb8aa3b, v27
	v_exp_f32_e32 v27, v27
	v_mul_f32_e32 v26, 0x3fb8aa3b, v26
	v_exp_f32_e32 v26, v26
	v_and_b32_e32 v29, 0xffff0000, v24
	v_add_f32_e32 v24, 1.0, v27
	v_rcp_f32_e32 v56, v24
	v_add_f32_e32 v24, 1.0, v26
	v_rcp_f32_e32 v57, v24
	v_cvt_f32_f16_sdwa v24, v52 dst_sel:DWORD dst_unused:UNUSED_PAD src0_sel:WORD_1
	v_cvt_f32_f16_e32 v27, v52
	v_cvt_f32_f16_e32 v68, v25
	v_lshlrev_b32_e32 v26, 16, v53
	v_mul_f32_e32 v24, 0x3fb8aa3b, v24
	v_exp_f32_e32 v24, v24
	v_mul_f32_e32 v27, 0x3fb8aa3b, v27
	v_exp_f32_e32 v52, v27
	v_and_b32_e32 v27, 0xffff0000, v53
	v_add_f32_e32 v24, 1.0, v24
	v_rcp_f32_e32 v53, v24
	v_mul_f32_e32 v24, 0x3fb8aa3b, v68
	v_exp_f32_e32 v68, v24
	v_cvt_f32_f16_sdwa v69, v25 dst_sel:DWORD dst_unused:UNUSED_PAD src0_sel:WORD_1
	v_lshlrev_b32_e32 v24, 16, v51
	v_and_b32_e32 v25, 0xffff0000, v51
	v_add_f32_e32 v51, 1.0, v68
	v_mul_f32_e32 v68, 0x3fb8aa3b, v69
	v_exp_f32_e32 v69, v68
	v_cvt_f32_f16_e32 v72, v50
	v_cvt_f32_f16_sdwa v50, v50 dst_sel:DWORD dst_unused:UNUSED_PAD src0_sel:WORD_1
	v_rcp_f32_e32 v68, v51
	v_add_f32_e32 v51, 1.0, v69
	v_mul_f32_e32 v69, 0x3fb8aa3b, v72
	v_mul_f32_e32 v50, 0x3fb8aa3b, v50
	v_exp_f32_e32 v72, v69
	v_exp_f32_e32 v73, v50
	ds_write_b128 v115, v[4:7] offset:52224
	s_cmp_lg_u64 s[76:77], 0
	s_cbranch_scc1 .Lp9_np
	s_waitcnt vmcnt(18)
	s_branch .Lp9_wd

; #define LAS __attribute__((address_space(3)))
; DI float h2f(unsigned short u) { return (float)__builtin_bit_cast(_Float16, u); }
; DI unsigned pk2(float lo, float hi) { f32x2 v = {lo, hi}; bf2_t b = __builtin_convertvector(v, bf2_t); return __builtin_bit_cast(unsigned, b); }
; DI float fexp(float x) { return __builtin_amdgcn_exp2f(x * 1.4426950408889634f); }
; DI float sigmoidf_(float x) { return frcp(1.f + fexp(-x)); }
; DI void hgC_item(LAS unsigned char* lds, unsigned char* ws, unsigned char* ob, int item, const float* ng, int dummy, const unsigned (&lfr)[16], const unsigned (&qvr)[16], const u32x4 (&ivw)[2], const float* lbp) {
;     ...
;             const float om0 = (1.f - lb2[0]) * sigmoidf_(-h2f((unsigned short)(lfr[i] & 0xffffu)));
;             const float om1 = (1.f - lb2[1]) * sigmoidf_(-h2f((unsigned short)(lfr[i] >> 16)));
;             kk0[i] = om0; kk1[i] = om1;
;             run0 += flog(1.f - om0); run1 += flog(1.f - om1);
;             cs0[i] = run0; cs1[i] = run1;
;             q0v[i] = bflo(qvr[i]); q1v[i] = bfhi(qvr[i]);
;         }
;         *(LAS f32x2*)(tot + tq * 128 + 2 * kp) = (f32x2){run0, run1};
;     }
;     hg_iv_store(VTs, ivw);
; #pragma unroll
;     for (int j = 0; j < 4; ++j) { const int id = tid + 512 * j; *(LAS u32x4*)(SS + (id >> 4) * HROW + (id & 15) * 16) = sreg[j]; }
;     __syncthreads();
;     {
;         float off0 = 0.f, off1 = 0.f, bref0 = 0.f, bref1 = 0.f;
; #pragma unroll
;         for (int q = 0; q < 8; ++q) {
;             const f32x2 tv = *(LAS f32x2*)(tot + q * 128 + 2 * kp);
;             if (q < tq) { off0 += tv[0]; off1 += tv[1]; }
;             if (q < 4) { bref0 += tv[0]; bref1 += tv[1]; }
;         }
; #pragma unroll
;         for (int i = 0; i < 8; ++i) {
;             const int t = tq * 8 + i;
;             const float bb0 = off0 + cs0[i], bb1 = off1 + cs1[i];
;             const float qi0 = q0v[i] * fexp(bb0), qi1 = q1v[i] * fexp(bb1);
;             const float qa0 = q0v[i] * fexp(fminf(bb0 - bref0, 80.f)), qa1 = q1v[i] * fexp(fminf(bb1 - bref1, 80.f));
;             const float ka0 = kk0[i] * fexp(fminf(bref0 - bb0, 80.f)), ka1 = kk1[i] * fexp(fminf(bref1 - bb1, 80.f));
;             *(LAS unsigned*)(QI + t * HROW + kp * 4) = pk2(qi0, qi1);
;             *(LAS unsigned*)(QA + t * HROW + kp * 4) = pk2(qa0, qa1);
;             *(LAS unsigned*)(KA + t * HROW + kp * 4) = pk2(ka0, ka1);
;         }
.Lp9_wd:
	v_pk_add_f32 v[4:5], v[58:59], 1.0 op_sel_hi:[1,0] neg_lo:[1,0] neg_hi:[1,0]
	v_rcp_f32_e32 v69, v51
	v_add_f32_e32 v50, 1.0, v72
	v_add_f32_e32 v51, 1.0, v73
	v_pk_mul_f32 v[72:73], v[4:5], v[60:61]
	v_pk_mul_f32 v[74:75], v[4:5], v[62:63]
	v_sub_f32_e32 v6, 1.0, v72
	v_sub_f32_e32 v7, 1.0, v73
	v_log_f32_e32 v6, v6
	v_log_f32_e32 v7, v7
	v_sub_f32_e32 v58, 1.0, v74
	v_sub_f32_e32 v59, 1.0, v75
	v_log_f32_e32 v58, v58
	v_log_f32_e32 v59, v59
	v_add_f32_e32 v52, 1.0, v52
	v_pk_mul_f32 v[64:65], v[4:5], v[64:65]
	v_rcp_f32_e32 v52, v52
	v_sub_f32_e32 v60, 1.0, v64
	v_log_f32_e32 v62, v60
	v_sub_f32_e32 v60, 1.0, v65
	v_pk_fma_f32 v[76:77], v[6:7], s[72:73], 0 op_sel_hi:[1,0,0]
	v_log_f32_e32 v63, v60
	v_pk_fma_f32 v[78:79], v[58:59], s[72:73], v[76:77] op_sel_hi:[1,0,1]
	v_pk_mul_f32 v[58:59], v[4:5], v[56:57]
	v_pk_mul_f32 v[52:53], v[4:5], v[52:53]
	v_sub_f32_e32 v6, 1.0, v58
	v_log_f32_e32 v56, v6
	v_sub_f32_e32 v6, 1.0, v59
	v_rcp_f32_e32 v50, v50
	v_rcp_f32_e32 v51, v51
	v_pk_mul_f32 v[60:61], v[4:5], v[66:67]
	v_log_f32_e32 v57, v6
	v_sub_f32_e32 v6, 1.0, v52
	v_sub_f32_e32 v66, 1.0, v60
	v_sub_f32_e32 v67, 1.0, v61
	v_pk_fma_f32 v[136:137], v[62:63], s[72:73], v[78:79] op_sel_hi:[1,0,1]
	v_log_f32_e32 v62, v6
	v_sub_f32_e32 v6, 1.0, v53
	v_log_f32_e32 v66, v66
	v_log_f32_e32 v67, v67
	v_log_f32_e32 v63, v6
	v_pk_mul_f32 v[6:7], v[4:5], v[68:69]
	v_pk_mul_f32 v[4:5], v[4:5], v[50:51]
	v_sub_f32_e32 v68, 1.0, v6
	v_log_f32_e32 v138, v68
	v_sub_f32_e32 v68, 1.0, v7
	v_log_f32_e32 v139, v68
	v_sub_f32_e32 v50, 1.0, v4
	v_sub_f32_e32 v51, 1.0, v5
	v_pk_fma_f32 v[66:67], v[66:67], s[72:73], v[136:137] op_sel_hi:[1,0,1]
	v_log_f32_e32 v50, v50
	v_log_f32_e32 v51, v51
	v_pk_fma_f32 v[68:69], v[56:57], s[72:73], v[66:67] op_sel_hi:[1,0,1]
	s_ashr_i32 s90, s97, 2
	v_pk_fma_f32 v[62:63], v[62:63], s[72:73], v[68:69] op_sel_hi:[1,0,1]
	s_lshl_b32 s68, s90, 5
	v_pk_fma_f32 v[56:57], v[138:139], s[72:73], v[62:63] op_sel_hi:[1,0,1]
	s_cmp_lt_i32 s90, 0
	v_pk_fma_f32 v[50:51], v[50:51], s[72:73], v[56:57] op_sel_hi:[1,0,1]
	ds_write_b64 v104, v[50:51]
	ds_write_b128 v116, v[0:3] offset:52224
	v_add_u32_e32 v0, v105, v106
	v_add_u32_e32 v1, v105, v107
	ds_write_b128 v0, v[8:11]
	ds_write_b128 v1, v[12:15]
	ds_write_b128 v0, v[16:19] offset:17408
	ds_write_b128 v117, v[20:23]
	s_waitcnt lgkmcnt(0)
	s_barrier
	ds_read2st64_b64 v[8:11], v103 offset1:1
	ds_read2st64_b64 v[12:15], v103 offset0:2 offset1:3
	v_lshlrev_b32_e32 v2, 16, v71
	v_and_b32_e32 v3, 0xffff0000, v71
	v_lshlrev_b32_e32 v0, 16, v70
	s_waitcnt lgkmcnt(1)
	v_add_f32_e32 v1, 0, v8
	v_cndmask_b32_e64 v16, v1, 0, s[4:5]
	v_add_f32_e32 v8, 0, v9
	v_add_f32_e32 v17, v10, v16
	v_cndmask_b32_e64 v9, v8, 0, s[4:5]
	v_cndmask_b32_e64 v16, v16, v17, s[6:7]
	v_add_f32_e32 v18, v11, v9
	v_add_f32_e32 v1, v1, v10
	s_waitcnt lgkmcnt(0)
	v_add_f32_e32 v10, v12, v16
	v_cndmask_b32_e64 v9, v9, v18, s[6:7]
	v_cndmask_b32_e64 v10, v16, v10, s[8:9]
	ds_read2st64_b64 v[16:19], v103 offset0:4 offset1:5
	v_add_f32_e32 v8, v8, v11
	v_add_f32_e32 v11, v13, v9
	v_cndmask_b32_e64 v20, v9, v11, s[8:9]
	v_add_f32_e32 v11, v1, v12
	v_add_f32_e32 v9, v8, v13
	v_add_f32_e32 v1, v14, v10
	v_add_f32_e32 v8, v15, v20
	v_cndmask_b32_e64 v8, v20, v8, s[10:11]
	v_cndmask_b32_e64 v1, v10, v1, s[10:11]
	ds_read2st64_b64 v[20:23], v103 offset0:6 offset1:7
	s_waitcnt lgkmcnt(1)
	v_add_f32_e32 v10, v16, v1
	v_add_f32_e32 v12, v17, v8
	v_cndmask_b32_e64 v8, v8, v12, s[12:13]
	v_cndmask_b32_e64 v1, v1, v10, s[12:13]
	v_add_f32_e32 v10, v18, v1
	v_add_f32_e32 v12, v19, v8
	v_cndmask_b32_e64 v8, v8, v12, s[14:15]
	v_cndmask_b32_e64 v1, v1, v10, s[14:15]
	s_waitcnt lgkmcnt(0)
	v_add_f32_e32 v10, v20, v1
	v_add_f32_e32 v12, v21, v8
	v_cndmask_b32_e64 v8, v8, v12, s[16:17]
	v_cndmask_b32_e64 v1, v1, v10, s[16:17]
	v_add_f32_e32 v10, v22, v1
	v_add_f32_e32 v12, v23, v8
	v_cndmask_b32_e64 v8, v8, v12, s[18:19]
	v_cndmask_b32_e64 v10, v1, v10, s[18:19]
	v_mov_b32_e32 v12, v76
	v_mov_b32_e32 v13, v14
	v_pk_add_f32 v[12:13], v[12:13], v[10:11]
	v_mov_b32_e32 v14, v77
	v_pk_add_f32 v[14:15], v[14:15], v[8:9]
	v_mul_f32_e32 v1, 0x3fb8aa3b, v12
	v_exp_f32_e32 v16, v1
	v_mul_f32_e32 v1, 0x3fb8aa3b, v14
	v_exp_f32_e32 v17, v1
	v_sub_f32_e32 v1, v12, v13
	v_min_f32_e32 v1, 0x42a00000, v1
	v_mul_f32_e32 v1, 0x3fb8aa3b, v1
	v_exp_f32_e32 v18, v1
	v_sub_f32_e32 v1, v14, v15
	v_min_f32_e32 v1, 0x42a00000, v1
	v_mul_f32_e32 v1, 0x3fb8aa3b, v1
	v_exp_f32_e32 v19, v1
	v_sub_f32_e32 v1, v13, v12
	v_min_f32_e32 v1, 0x42a00000, v1
	v_pk_mul_f32 v[16:17], v[16:17], v[54:55]
	v_pk_mul_f32 v[18:19], v[18:19], v[54:55]
	v_add_f32_e32 v12, v78, v10
	v_mul_f32_e32 v1, 0x3fb8aa3b, v1
	v_cvt_pk_bf16_f32 v9, v16, v17
	v_cvt_pk_bf16_f32 v11, v18, v19
	v_mul_f32_e32 v16, 0x3fb8aa3b, v12
	v_sub_f32_e32 v18, v12, v13
	v_sub_f32_e32 v12, v13, v12
	v_exp_f32_e32 v20, v1
	v_sub_f32_e32 v1, v15, v14
	v_add_f32_e32 v14, v79, v8
	v_min_f32_e32 v12, 0x42a00000, v12
	v_sub_f32_e32 v19, v14, v15
	v_mul_f32_e32 v12, 0x3fb8aa3b, v12
	v_min_f32_e32 v1, 0x42a00000, v1
	v_mul_f32_e32 v17, 0x3fb8aa3b, v14
	v_min_f32_e32 v18, 0x42a00000, v18
	v_min_f32_e32 v19, 0x42a00000, v19
	v_exp_f32_e32 v22, v12
	v_sub_f32_e32 v12, v15, v14
	v_mul_f32_e32 v1, 0x3fb8aa3b, v1
	v_exp_f32_e32 v16, v16
	v_exp_f32_e32 v17, v17
	v_mul_f32_e32 v18, 0x3fb8aa3b, v18
	v_mul_f32_e32 v19, 0x3fb8aa3b, v19
	v_min_f32_e32 v12, 0x42a00000, v12
	v_exp_f32_e32 v21, v1
	v_exp_f32_e32 v18, v18
	v_exp_f32_e32 v19, v19
	v_mul_f32_e32 v12, 0x3fb8aa3b, v12
	v_exp_f32_e32 v23, v12
	v_pk_mul_f32 v[16:17], v[16:17], v[48:49]
	v_pk_mul_f32 v[20:21], v[72:73], v[20:21]
	v_pk_mul_f32 v[18:19], v[18:19], v[48:49]
; #define LAS __attribute__((address_space(3)))
; DI unsigned pk2(float lo, float hi) { f32x2 v = {lo, hi}; bf2_t b = __builtin_convertvector(v, bf2_t); return __builtin_bit_cast(unsigned, b); }
; DI float fexp(float x) { return __builtin_amdgcn_exp2f(x * 1.4426950408889634f); }
; DI void hgC_item(LAS unsigned char* lds, unsigned char* ws, unsigned char* ob, int item, const float* ng, int dummy, const unsigned (&lfr)[16], const unsigned (&qvr)[16], const u32x4 (&ivw)[2], const float* lbp) {
;     ...
; #pragma unroll
;         for (int i = 0; i < 8; ++i) {
;             const int t = tq * 8 + i;
;             const float bb0 = off0 + cs0[i], bb1 = off1 + cs1[i];
;             const float qi0 = q0v[i] * fexp(bb0), qi1 = q1v[i] * fexp(bb1);
;             const float qa0 = q0v[i] * fexp(fminf(bb0 - bref0, 80.f)), qa1 = q1v[i] * fexp(fminf(bb1 - bref1, 80.f));
;             const float ka0 = kk0[i] * fexp(fminf(bref0 - bb0, 80.f)), ka1 = kk1[i] * fexp(fminf(bref1 - bb1, 80.f));
;             *(LAS unsigned*)(QI + t * HROW + kp * 4) = pk2(qi0, qi1);
;             *(LAS unsigned*)(QA + t * HROW + kp * 4) = pk2(qa0, qa1);
;             *(LAS unsigned*)(KA + t * HROW + kp * 4) = pk2(ka0, ka1);
;         }
	v_cvt_pk_bf16_f32 v14, v16, v17
	v_cvt_pk_bf16_f32 v12, v20, v21
	v_pk_mul_f32 v[20:21], v[74:75], v[22:23]
	ds_write2_b32 v118, v9, v14 offset1:68
	v_cvt_pk_bf16_f32 v9, v18, v19
	v_add_u32_e32 v14, 0x4400, v118
	ds_write2_b32 v14, v11, v9 offset1:68
	v_cvt_pk_bf16_f32 v9, v20, v21
	v_add_f32_e32 v20, v136, v10
	v_add_f32_e32 v21, v137, v8
	v_sub_f32_e32 v18, v20, v13
	v_sub_f32_e32 v19, v21, v15
	v_min_f32_e32 v18, 0x42a00000, v18
	v_min_f32_e32 v19, 0x42a00000, v19
	v_mul_f32_e32 v18, 0x3fb8aa3b, v18
	v_mul_f32_e32 v19, 0x3fb8aa3b, v19
	v_mul_f32_e32 v16, 0x3fb8aa3b, v20
	v_mul_f32_e32 v17, 0x3fb8aa3b, v21
	v_exp_f32_e32 v18, v18
	v_exp_f32_e32 v19, v19
	v_exp_f32_e32 v16, v16
	v_exp_f32_e32 v17, v17
	v_add_u32_e32 v11, 0x8800, v118
	v_pk_mul_f32 v[18:19], v[18:19], v[30:31]
	v_add_f32_e32 v22, v66, v10
	v_add_f32_e32 v23, v67, v8
	ds_write2_b32 v11, v12, v9 offset1:68
	v_pk_mul_f32 v[16:17], v[16:17], v[30:31]
	v_cvt_pk_bf16_f32 v12, v18, v19
	v_sub_f32_e32 v18, v22, v13
	v_sub_f32_e32 v19, v23, v15
	v_cvt_pk_bf16_f32 v9, v16, v17
	v_mul_f32_e32 v16, 0x3fb8aa3b, v22
	v_mul_f32_e32 v17, 0x3fb8aa3b, v23
	v_min_f32_e32 v18, 0x42a00000, v18
	v_min_f32_e32 v19, 0x42a00000, v19
	v_exp_f32_e32 v16, v16
	v_exp_f32_e32 v17, v17
	v_mul_f32_e32 v18, 0x3fb8aa3b, v18
	v_mul_f32_e32 v19, 0x3fb8aa3b, v19
	v_exp_f32_e32 v18, v18
	v_exp_f32_e32 v19, v19
	v_sub_f32_e32 v20, v13, v20
	v_sub_f32_e32 v21, v15, v21
	v_min_f32_e32 v20, 0x42a00000, v20
	v_min_f32_e32 v21, 0x42a00000, v21
	v_sub_f32_e32 v22, v13, v22
	v_sub_f32_e32 v23, v15, v23
	v_pk_mul_f32 v[16:17], v[16:17], v[28:29]
	v_mul_f32_e32 v20, 0x3fb8aa3b, v20
	v_mul_f32_e32 v21, 0x3fb8aa3b, v21
	v_min_f32_e32 v22, 0x42a00000, v22
	v_min_f32_e32 v23, 0x42a00000, v23
	v_pk_mul_f32 v[18:19], v[18:19], v[28:29]
	v_cvt_pk_bf16_f32 v16, v16, v17
	v_exp_f32_e32 v20, v20
	v_exp_f32_e32 v21, v21
	v_mul_f32_e32 v22, 0x3fb8aa3b, v22
	v_mul_f32_e32 v23, 0x3fb8aa3b, v23
	ds_write2_b32 v118, v9, v16 offset0:136 offset1:204
	v_cvt_pk_bf16_f32 v9, v18, v19
	v_exp_f32_e32 v22, v22
	v_exp_f32_e32 v23, v23
	ds_write2_b32 v14, v12, v9 offset0:136 offset1:204
	v_add_f32_e32 v12, v68, v10
	v_add_f32_e32 v14, v69, v8
	v_sub_f32_e32 v18, v12, v13
	v_sub_f32_e32 v19, v14, v15
	v_mul_f32_e32 v16, 0x3fb8aa3b, v12
	v_min_f32_e32 v18, 0x42a00000, v18
	v_min_f32_e32 v19, 0x42a00000, v19
	v_sub_f32_e32 v12, v13, v12
	v_pk_mul_f32 v[20:21], v[64:65], v[20:21]
	v_mul_f32_e32 v17, 0x3fb8aa3b, v14
	v_mul_f32_e32 v18, 0x3fb8aa3b, v18
	v_mul_f32_e32 v19, 0x3fb8aa3b, v19
	v_min_f32_e32 v12, 0x42a00000, v12
	v_cvt_pk_bf16_f32 v30, v20, v21
	v_pk_mul_f32 v[20:21], v[60:61], v[22:23]
	v_exp_f32_e32 v16, v16
	v_exp_f32_e32 v17, v17
	v_exp_f32_e32 v18, v18
	v_exp_f32_e32 v19, v19
	v_mul_f32_e32 v12, 0x3fb8aa3b, v12
	v_cvt_pk_bf16_f32 v9, v20, v21
	v_exp_f32_e32 v20, v12
	v_sub_f32_e32 v12, v15, v14
	v_min_f32_e32 v12, 0x42a00000, v12
	v_mul_f32_e32 v12, 0x3fb8aa3b, v12
	v_exp_f32_e32 v21, v12
	v_pk_mul_f32 v[16:17], v[16:17], v[26:27]
	v_pk_mul_f32 v[18:19], v[18:19], v[26:27]
	v_add_f32_e32 v12, v62, v10
	ds_write2_b32 v11, v30, v9 offset0:136 offset1:204
	v_cvt_pk_bf16_f32 v9, v16, v17
	v_cvt_pk_bf16_f32 v11, v18, v19
	v_mul_f32_e32 v16, 0x3fb8aa3b, v12
	v_sub_f32_e32 v18, v12, v13
	v_sub_f32_e32 v12, v13, v12
	v_min_f32_e32 v12, 0x42a00000, v12
	v_add_f32_e32 v14, v63, v8
	v_mul_f32_e32 v12, 0x3fb8aa3b, v12
	v_sub_f32_e32 v19, v14, v15
	v_exp_f32_e32 v22, v12
	v_sub_f32_e32 v12, v15, v14
	v_mul_f32_e32 v17, 0x3fb8aa3b, v14
	v_min_f32_e32 v18, 0x42a00000, v18
	v_min_f32_e32 v19, 0x42a00000, v19
	v_min_f32_e32 v12, 0x42a00000, v12
	v_exp_f32_e32 v16, v16
	v_exp_f32_e32 v17, v17
	v_mul_f32_e32 v18, 0x3fb8aa3b, v18
	v_mul_f32_e32 v19, 0x3fb8aa3b, v19
	v_mul_f32_e32 v12, 0x3fb8aa3b, v12
	v_exp_f32_e32 v18, v18
	v_exp_f32_e32 v19, v19
	v_exp_f32_e32 v23, v12
	v_pk_mul_f32 v[20:21], v[58:59], v[20:21]
	v_pk_mul_f32 v[16:17], v[16:17], v[24:25]
	v_cvt_pk_bf16_f32 v12, v20, v21
	v_pk_mul_f32 v[18:19], v[18:19], v[24:25]
	v_pk_mul_f32 v[20:21], v[52:53], v[22:23]
	v_cvt_pk_bf16_f32 v14, v16, v17
	v_add_u32_e32 v22, 0x400, v118
	ds_write2_b32 v22, v9, v14 offset0:16 offset1:84
	v_cvt_pk_bf16_f32 v9, v18, v19
	v_add_u32_e32 v14, 0x4800, v118
	ds_write2_b32 v14, v11, v9 offset0:16 offset1:84
	v_add_f32_e32 v11, v56, v10
	v_cvt_pk_bf16_f32 v9, v20, v21
	v_add_f32_e32 v21, v57, v8
	v_mul_f32_e32 v16, 0x3fb8aa3b, v11
	v_sub_f32_e32 v18, v11, v13
	v_sub_f32_e32 v11, v13, v11
	v_sub_f32_e32 v19, v21, v15
	v_min_f32_e32 v11, 0x42a00000, v11
	v_min_f32_e32 v18, 0x42a00000, v18
	v_min_f32_e32 v19, 0x42a00000, v19
	v_mul_f32_e32 v11, 0x3fb8aa3b, v11
	v_mul_f32_e32 v17, 0x3fb8aa3b, v21
	v_mul_f32_e32 v18, 0x3fb8aa3b, v18
	v_mul_f32_e32 v19, 0x3fb8aa3b, v19
	v_exp_f32_e32 v20, v11
	v_sub_f32_e32 v11, v15, v21
	v_exp_f32_e32 v16, v16
	v_exp_f32_e32 v17, v17
	v_exp_f32_e32 v18, v18
	v_exp_f32_e32 v19, v19
	v_min_f32_e32 v11, 0x42a00000, v11
	v_mul_f32_e32 v11, 0x3fb8aa3b, v11
	v_add_u32_e32 v23, 0x8c00, v118
	v_exp_f32_e32 v21, v11
	v_add_f32_e32 v10, v50, v10
	v_add_f32_e32 v11, v51, v8
	ds_write2_b32 v23, v12, v9 offset0:16 offset1:84
	v_sub_f32_e32 v8, v10, v13
	v_sub_f32_e32 v9, v11, v15
	v_pk_mul_f32 v[16:17], v[16:17], v[2:3]
	v_pk_mul_f32 v[2:3], v[18:19], v[2:3]
	v_min_f32_e32 v8, 0x42a00000, v8
	v_min_f32_e32 v9, 0x42a00000, v9
	v_cvt_pk_bf16_f32 v12, v16, v17
	v_cvt_pk_bf16_f32 v16, v2, v3
	v_mul_f32_e32 v2, 0x3fb8aa3b, v10
	v_mul_f32_e32 v3, 0x3fb8aa3b, v11
	v_mul_f32_e32 v8, 0x3fb8aa3b, v8
	v_mul_f32_e32 v9, 0x3fb8aa3b, v9
	v_sub_f32_e32 v10, v13, v10
	v_sub_f32_e32 v11, v15, v11
	v_exp_f32_e32 v2, v2
	v_exp_f32_e32 v3, v3
	v_exp_f32_e32 v8, v8
	v_exp_f32_e32 v9, v9
	v_min_f32_e32 v10, 0x42a00000, v10
	v_min_f32_e32 v11, 0x42a00000, v11
	v_mul_f32_e32 v10, 0x3fb8aa3b, v10
	v_mul_f32_e32 v11, 0x3fb8aa3b, v11
	v_exp_f32_e32 v10, v10
	v_exp_f32_e32 v11, v11
	v_and_b32_e32 v1, 0xffff0000, v70
	v_pk_mul_f32 v[2:3], v[2:3], v[0:1]
	v_pk_mul_f32 v[0:1], v[8:9], v[0:1]
	v_pk_mul_f32 v[6:7], v[6:7], v[20:21]
	v_cvt_pk_bf16_f32 v0, v0, v1
	v_pk_mul_f32 v[4:5], v[4:5], v[10:11]
	ds_write2_b32 v14, v16, v0 offset0:152 offset1:220
	v_lshl_or_b32 v16, s75, 5, v100
	v_cvt_pk_bf16_f32 v6, v6, v7
	v_cvt_pk_bf16_f32 v2, v2, v3
	v_cvt_pk_bf16_f32 v0, v4, v5
	v_mad_u32_u24 v30, v16, s96, v109
	ds_write2_b32 v22, v12, v2 offset0:152 offset1:220
	ds_write2_b32 v23, v6, v0 offset0:152 offset1:220
	s_waitcnt lgkmcnt(0)
	s_barrier
; #define LAS __attribute__((address_space(3)))
; DI void hgC_item(LAS unsigned char* lds, unsigned char* ws, unsigned char* ob, int item, const float* ng, int dummy, const unsigned (&lfr)[16], const unsigned (&qvr)[16], const u32x4 (&ivw)[2], const float* lbp) {
;     ...
;     f32x16 acc;
; #pragma unroll
;     for (int i = 0; i < 16; ++i) acc[i] = 0.f;
;     {
;         const LAS unsigned char* qp = QI + (32 * tb + r) * HROW + 16 * h2;
; #pragma unroll
;         for (int ks = 0; ks < 8; ++ks) {
;             const bf16x8 bq = *(const LAS bf16x8*)(qp + 32 * ks);
;             const bf16x8 sa = *(const LAS bf16x8*)(SS + (32 * vb + r) * HROW + 16 * h2 + 32 * ks);
;             acc = __builtin_amdgcn_mfma_f32_32x32x16_bf16(sa, bq, acc, 0, 0, 0);
;         }
;     }
;     for (int sb = 0; sb <= tb; ++sb) {
;         f32x16 AT;
; #pragma unroll
;         for (int i = 0; i < 16; ++i) AT[i] = 0.f;
;         const LAS unsigned char* kp = KA + (32 * sb + r) * HROW + 16 * h2;
;         const LAS unsigned char* qp = QA + (32 * tb + r) * HROW + 16 * h2;
; #pragma unroll
;         for (int ks = 0; ks < 8; ++ks) {
;             const bf16x8 a = *(const LAS bf16x8*)(kp + 32 * ks);
;             const bf16x8 bq = *(const LAS bf16x8*)(qp + 32 * ks);
;             AT = __builtin_amdgcn_mfma_f32_32x32x16_bf16(a, bq, AT, 0, 0, 0);
;         }
	ds_read_b128 v[0:3], v30
	v_or_b32_e32 v136, s68, v100
	v_mul_lo_u32 v17, v136, s96
	v_add_u32_e32 v93, 0, v17
	v_add_u32_e32 v31, v93, v108
	ds_read_b128 v[4:7], v31
	ds_read_b128 v[18:21], v31 offset:32
	ds_read_b128 v[22:25], v30 offset:32
	s_waitcnt lgkmcnt(2)
	v_mfma_f32_32x32x16_bf16 v[0:15], v[0:3], v[4:7], 0
	s_waitcnt lgkmcnt(0)
	v_mfma_f32_32x32x16_bf16 v[0:15], v[22:25], v[18:21], v[0:15]
	ds_read_b128 v[18:21], v30 offset:64
	ds_read_b128 v[22:25], v31 offset:64
	ds_read_b128 v[26:29], v31 offset:96
	ds_read_b128 v[48:51], v30 offset:96
	s_waitcnt lgkmcnt(2)
	v_mfma_f32_32x32x16_bf16 v[0:15], v[18:21], v[22:25], v[0:15]
	s_waitcnt lgkmcnt(0)
	v_mfma_f32_32x32x16_bf16 v[0:15], v[48:51], v[26:29], v[0:15]
	ds_read_b128 v[18:21], v30 offset:128
	ds_read_b128 v[22:25], v31 offset:128
	ds_read_b128 v[26:29], v31 offset:160
	ds_read_b128 v[48:51], v30 offset:160
	s_waitcnt lgkmcnt(2)
	v_mfma_f32_32x32x16_bf16 v[0:15], v[18:21], v[22:25], v[0:15]
	s_waitcnt lgkmcnt(0)
	v_mfma_f32_32x32x16_bf16 v[0:15], v[48:51], v[26:29], v[0:15]
	ds_read_b128 v[18:21], v30 offset:192
	ds_read_b128 v[22:25], v31 offset:192
	ds_read_b128 v[26:29], v31 offset:224
	ds_read_b128 v[48:51], v30 offset:224
	s_waitcnt lgkmcnt(2)
	v_mfma_f32_32x32x16_bf16 v[0:15], v[18:21], v[22:25], v[0:15]
	s_waitcnt lgkmcnt(0)
	v_mfma_f32_32x32x16_bf16 v[0:15], v[48:51], v[26:29], v[0:15]
	s_cbranch_scc1 .LBB0_1122
	v_add_u32_e32 v17, v88, v17
	ds_read_b128 v[76:79], v17 offset:17408
	ds_read_b128 v[72:75], v17 offset:17440
	ds_read_b128 v[68:71], v17 offset:17472
	ds_read_b128 v[64:67], v17 offset:17504
	ds_read_b128 v[60:63], v17 offset:17536
	ds_read_b128 v[56:59], v17 offset:17568
	ds_read_b128 v[52:55], v17 offset:17600
	ds_read_b128 v[48:51], v17 offset:17632
	s_cmp_lt_u32 s97, 4
	v_mul_u32_u24_e32 v137, 0x90, v16
	s_cbranch_scc1 .LBB0_1120
	v_add_u32_e32 v138, v113, v137
	v_mov_b32_e32 v139, v114
	s_mov_b32 s97, s90
